# phase_conv RMSNorm rows hand-scheduled; mlstm_out q-row, fragment and readout loads batched; s5 carry-in loads batched
# speedup vs baseline: 1.0301x; 1.0170x over previous
.LBB0_194:
	s_or_b64 exec, exec, s[18:19]
	v_ashrrev_i32_e32 v33, 6, v32
	v_ashrrev_i32_e32 v10, 7, v32
	s_waitcnt lgkmcnt(0)
	s_add_u32 s18, s16, 0x29240000
	v_lshlrev_b32_e32 v0, 1, v33
	v_ashrrev_i32_e32 v11, 31, v10
	s_addc_u32 s19, s17, 0
	v_and_b32_e32 v38, 2, v0
	v_lshlrev_b64 v[0:1], 13, v[10:11]
	s_lshl_b64 s[16:17], s[10:11], 15
	v_and_b32_e32 v12, 63, v32
	v_lshl_add_u64 v[0:1], s[18:19], 0, v[0:1]
	s_add_u32 s20, s20, s16
	v_lshl_add_u64 v[0:1], v[0:1], 0, s[16:17]
	v_lshlrev_b32_e32 v8, 4, v12
	v_mov_b32_e32 v9, v169
	s_addc_u32 s21, s21, s17
	v_lshlrev_b32_e32 v168, 13, v38
	v_lshl_add_u64 v[6:7], v[0:1], 0, v[8:9]
	v_lshl_add_u64 v[0:1], s[20:21], 0, v[168:169]
	v_lshl_add_u64 v[0:1], v[0:1], 0, v[8:9]
	s_mov_b64 s[20:21], 0x2a240000
	v_lshl_add_u64 v[30:31], v[0:1], 0, s[20:21]
	s_mov_b32 s20, 0x2a241000
	v_add_co_u32_e32 v34, vcc, s20, v0
	s_mov_b32 s20, 0x2a242000
	s_nop 0
	v_addc_co_u32_e32 v35, vcc, 0, v1, vcc
	s_barrier
	v_add_co_u32_e32 v36, vcc, s20, v0
	s_mov_b32 s20, 0x2a243000
	s_nop 0
	v_addc_co_u32_e32 v37, vcc, 0, v1, vcc
	v_add_co_u32_e32 v0, vcc, s20, v0
	s_nop 1
	v_addc_co_u32_e32 v1, vcc, 0, v1, vcc
	global_load_dwordx4 v[120:123], v[6:7], off
	global_load_dwordx4 v[124:127], v[6:7], off offset:1024
	global_load_dwordx4 v[128:131], v[6:7], off offset:2048
	global_load_dwordx4 v[132:135], v[6:7], off offset:3072
	global_load_dwordx4 v[152:155], v[34:35], off offset:-4096
	global_load_dwordx4 v[156:159], v[30:31], off offset:1024
	global_load_dwordx4 v[160:163], v[30:31], off offset:2048
	global_load_dwordx4 v[164:167], v[30:31], off offset:3072
	global_load_dwordx4 v[192:195], v[0:1], off offset:-4096
	global_load_dwordx4 v[196:199], v[36:37], off offset:1024
	global_load_dwordx4 v[200:203], v[36:37], off offset:2048
	global_load_dwordx4 v[204:207], v[36:37], off offset:3072
	v_add_co_u32_e32 v6, vcc, s3, v6
	s_nop 1
	v_addc_co_u32_e32 v7, vcc, 0, v7, vcc
	global_load_dwordx4 v[136:139], v[6:7], off
	global_load_dwordx4 v[140:143], v[6:7], off offset:1024
	global_load_dwordx4 v[144:147], v[6:7], off offset:2048
	global_load_dwordx4 v[148:151], v[6:7], off offset:3072
	global_load_dwordx4 v[176:179], v[34:35], off
	global_load_dwordx4 v[180:183], v[34:35], off offset:1024
	global_load_dwordx4 v[184:187], v[34:35], off offset:2048
	global_load_dwordx4 v[188:191], v[34:35], off offset:3072
	global_load_dwordx4 v[208:211], v[0:1], off
	global_load_dwordx4 v[212:215], v[0:1], off offset:1024
	global_load_dwordx4 v[216:219], v[0:1], off offset:2048
	global_load_dwordx4 v[220:223], v[0:1], off offset:3072
	v_lshrrev_b32_e32 v9, 2, v32
	v_and_b32_e32 v66, 12, v9
	v_lshl_or_b32 v13, v10, 4, v66
	v_lshl_add_u32 v11, v13, 2, 0
	v_and_b32_e32 v63, 15, v32
	v_lshl_or_b32 v10, v38, 4, v63
	v_lshl_add_u32 v9, v10, 2, 0
	v_cmp_le_i32_e32 vcc, v10, v13
	s_waitcnt vmcnt(0)
	v_mfma_f32_16x16x32_bf16 v[14:17], v[120:123], v[152:155], 0
	v_mfma_f32_16x16x32_bf16 v[18:21], v[120:123], v[192:195], 0
	v_mfma_f32_16x16x32_bf16 v[14:17], v[124:127], v[156:159], v[14:17]
	v_mfma_f32_16x16x32_bf16 v[18:21], v[124:127], v[196:199], v[18:21]
	v_mfma_f32_16x16x32_bf16 v[14:17], v[128:131], v[160:163], v[14:17]
	v_mfma_f32_16x16x32_bf16 v[18:21], v[128:131], v[200:203], v[18:21]
	v_mfma_f32_16x16x32_bf16 v[14:17], v[132:135], v[164:167], v[14:17]
	v_mfma_f32_16x16x32_bf16 v[18:21], v[132:135], v[204:207], v[18:21]
	v_mfma_f32_16x16x32_bf16 v[14:17], v[136:139], v[176:179], v[14:17]
	v_mfma_f32_16x16x32_bf16 v[18:21], v[136:139], v[208:211], v[18:21]
	v_mfma_f32_16x16x32_bf16 v[14:17], v[140:143], v[180:183], v[14:17]
	v_mfma_f32_16x16x32_bf16 v[18:21], v[140:143], v[212:215], v[18:21]
	v_mfma_f32_16x16x32_bf16 v[14:17], v[144:147], v[184:187], v[14:17]
	v_mfma_f32_16x16x32_bf16 v[18:21], v[144:147], v[216:219], v[18:21]
	v_mfma_f32_16x16x32_bf16 v[4:7], v[148:151], v[188:191], v[14:17]
	s_nop 2
	ds_read2st64_b32 v[14:15], v11 offset0:36 offset1:38
	s_waitcnt lgkmcnt(0)
	v_sub_f32_e32 v16, v14, v15
	v_mfma_f32_16x16x32_bf16 v[0:3], v[148:151], v[220:223], v[18:21]
	v_mov_b32_e32 v15, 0
	v_mov_b32_e32 v14, 0
	s_and_saveexec_b64 s[20:21], vcc
	s_cbranch_execz .LBB0_196
	ds_read_b32 v14, v9 offset:9472
	s_waitcnt lgkmcnt(0)
	v_add_f32_e32 v14, v16, v14
	v_mul_f32_e32 v14, 0x3fb8aa3b, v14
	v_exp_f32_e32 v14, v14
	s_nop 0
	v_mul_f32_e32 v14, v4, v14

.LBB0_212:
	s_or_b64 exec, exec, s[20:21]
	s_load_dwordx2 s[6:7], s[0:1], 0x150
	s_and_b32 s22, s10, 0xffffff80
	s_lshl_b64 s[20:21], s[10:11], 10
	v_mov_b32_e32 v9, v169
	v_lshlrev_b32_e32 v4, 3, v12
	s_waitcnt lgkmcnt(0)
	s_add_u32 s6, s6, s20
	s_addc_u32 s7, s7, s21
	v_lshl_add_u64 v[0:1], s[6:7], 0, v[8:9]
	v_lshlrev_b32_e32 v6, 3, v33
	v_lshrrev_b32_e32 v7, 3, v12
	v_lshlrev_b32_e32 v9, 2, v33
	v_and_or_b32 v9, v9, 24, v7
	v_and_b32_e32 v7, 48, v4
	v_add_u32_e32 v4, s24, v6
	v_ashrrev_i32_e32 v4, 6, v4
	v_lshlrev_b32_e32 v5, 2, v12
	v_add_u32_e32 v4, s22, v4
	v_and_b32_e32 v13, 4, v5
	v_ashrrev_i32_e32 v5, 31, v4
	v_lshlrev_b64 v[4:5], 15, v[4:5]
	v_and_or_b32 v10, v6, 8, v7
	v_lshlrev_b32_e32 v168, 10, v9
	v_lshl_add_u64 v[4:5], s[18:19], 0, v[4:5]
	v_lshl_add_u64 v[4:5], v[4:5], 0, v[168:169]
	v_lshlrev_b32_e32 v168, 4, v10
	v_lshl_add_u64 v[10:11], v[4:5], 0, v[168:169]
	v_lshlrev_b32_e32 v168, 1, v13
	v_add_co_u32_e32 v0, vcc, 0x2d301000, v0
	v_lshl_add_u64 v[10:11], v[10:11], 0, v[168:169]
	s_nop 0
	v_addc_co_u32_e32 v1, vcc, 0, v1, vcc
	v_or_b32_e32 v212, 1, v6
	v_and_or_b32 v212, v212, 9, v7
	v_lshlrev_b32_e32 v212, 4, v212
	v_mov_b32_e32 v213, v169
	v_lshl_add_u64 v[212:213], v[4:5], 0, v[212:213]
	v_lshl_add_u64 v[212:213], v[212:213], 0, v[168:169]
	global_load_dwordx2 v[212:213], v[212:213], off
	v_or_b32_e32 v214, 2, v6
	v_and_or_b32 v214, v214, 10, v7
	v_lshlrev_b32_e32 v214, 4, v214
	v_mov_b32_e32 v215, v169
	v_lshl_add_u64 v[214:215], v[4:5], 0, v[214:215]
	v_lshl_add_u64 v[214:215], v[214:215], 0, v[168:169]
	global_load_dwordx2 v[214:215], v[214:215], off
	v_or_b32_e32 v216, 3, v6
	v_and_or_b32 v216, v216, 11, v7
	v_lshlrev_b32_e32 v216, 4, v216
	v_mov_b32_e32 v217, v169
	v_lshl_add_u64 v[216:217], v[4:5], 0, v[216:217]
	v_lshl_add_u64 v[216:217], v[216:217], 0, v[168:169]
	global_load_dwordx2 v[216:217], v[216:217], off
	v_or_b32_e32 v218, 4, v6
	v_and_or_b32 v218, v218, 12, v7
	v_lshlrev_b32_e32 v218, 4, v218
	v_mov_b32_e32 v219, v169
	v_lshl_add_u64 v[218:219], v[4:5], 0, v[218:219]
	v_lshl_add_u64 v[218:219], v[218:219], 0, v[168:169]
	global_load_dwordx2 v[218:219], v[218:219], off
	v_or_b32_e32 v220, 5, v6
	v_and_or_b32 v220, v220, 13, v7
	v_lshlrev_b32_e32 v220, 4, v220
	v_mov_b32_e32 v221, v169
	v_lshl_add_u64 v[220:221], v[4:5], 0, v[220:221]
	v_lshl_add_u64 v[220:221], v[220:221], 0, v[168:169]
	global_load_dwordx2 v[220:221], v[220:221], off
	v_or_b32_e32 v222, 6, v6
	v_and_or_b32 v222, v222, 14, v7
	v_lshlrev_b32_e32 v222, 4, v222
	v_mov_b32_e32 v223, v169
	v_lshl_add_u64 v[222:223], v[4:5], 0, v[222:223]
	v_lshl_add_u64 v[222:223], v[222:223], 0, v[168:169]
	global_load_dwordx2 v[222:223], v[222:223], off
	v_or_b32_e32 v224, 7, v6
	v_and_or_b32 v224, v224, 15, v7
	v_lshlrev_b32_e32 v224, 4, v224
	v_mov_b32_e32 v225, v169
	v_lshl_add_u64 v[224:225], v[4:5], 0, v[224:225]
	v_lshl_add_u64 v[224:225], v[224:225], 0, v[168:169]
	global_load_dwordx2 v[224:225], v[224:225], off
	global_load_dwordx2 v[10:11], v[10:11], off
	v_cmp_eq_u32_e32 vcc, 0, v12
	global_load_dwordx4 v[0:3], v[0:1], off offset:2048
	s_waitcnt vmcnt(1)
	v_lshlrev_b32_e32 v9, 16, v10
	v_and_b32_e32 v10, 0xffff0000, v10
	s_waitcnt vmcnt(0)
	v_mul_f32_e32 v10, v1, v10
	v_fmac_f32_e32 v10, v0, v9
	v_lshlrev_b32_e32 v9, 16, v11
	v_fmac_f32_e32 v10, v2, v9
	v_and_b32_e32 v9, 0xffff0000, v11
	v_fmac_f32_e32 v10, v3, v9
	s_nop 1
	v_add_f32_dpp v9, v10, v10 quad_perm:[1,0,3,2] row_mask:0xf bank_mask:0xf bound_ctrl:1
	s_nop 1
	v_add_f32_dpp v9, v9, v9 quad_perm:[2,3,0,1] row_mask:0xf bank_mask:0xf bound_ctrl:1
	s_nop 1
	v_add_f32_dpp v9, v9, v9 row_half_mirror row_mask:0xf bank_mask:0xf bound_ctrl:1
	s_nop 1
	v_add_f32_dpp v9, v9, v9 row_mirror row_mask:0xf bank_mask:0xf bound_ctrl:1
	s_nop 0
	v_readlane_b32 s6, v9, 0
	v_readlane_b32 s11, v9, 16
	v_readlane_b32 s7, v9, 32
	v_readlane_b32 s20, v9, 48
	v_lshl_add_u32 v9, v6, 2, 0
	s_and_saveexec_b64 s[18:19], vcc
	v_mov_b32_e32 v10, s11
	v_mov_b32_e32 v11, s20
	v_pk_add_f32 v[10:11], s[6:7], v[10:11]
	s_nop 0
	v_add_f32_e32 v10, v10, v11
	ds_write_b32 v9, v10 offset:10496
	s_or_b64 exec, exec, s[18:19]
	v_mov_b32_e32 v10, v212
	v_mov_b32_e32 v11, v213
	s_waitcnt vmcnt(0)
	v_lshlrev_b32_e32 v13, 16, v10
	v_and_b32_e32 v10, 0xffff0000, v10
	v_mul_f32_e32 v10, v1, v10
	v_fmac_f32_e32 v10, v0, v13
	v_lshlrev_b32_e32 v13, 16, v11
	v_fmac_f32_e32 v10, v2, v13
	v_and_b32_e32 v11, 0xffff0000, v11
	v_fmac_f32_e32 v10, v3, v11
	s_nop 1
	v_add_f32_dpp v10, v10, v10 quad_perm:[1,0,3,2] row_mask:0xf bank_mask:0xf bound_ctrl:1
	s_nop 1
	v_add_f32_dpp v10, v10, v10 quad_perm:[2,3,0,1] row_mask:0xf bank_mask:0xf bound_ctrl:1
	s_nop 1
	v_add_f32_dpp v10, v10, v10 row_half_mirror row_mask:0xf bank_mask:0xf bound_ctrl:1
	s_nop 1
	v_add_f32_dpp v10, v10, v10 row_mirror row_mask:0xf bank_mask:0xf bound_ctrl:1
	s_nop 0
	v_readlane_b32 s18, v10, 0
	v_readlane_b32 s11, v10, 16
	v_readlane_b32 s19, v10, 32
	v_readlane_b32 s20, v10, 48
	s_and_saveexec_b64 s[6:7], vcc
	v_mov_b32_e32 v10, s11
	v_mov_b32_e32 v11, s20
	v_pk_add_f32 v[10:11], s[18:19], v[10:11]
	s_nop 0
	v_add_f32_e32 v10, v10, v11
	ds_write_b32 v9, v10 offset:10500
	s_or_b64 exec, exec, s[6:7]
	v_mov_b32_e32 v10, v214
	v_mov_b32_e32 v11, v215
	s_waitcnt vmcnt(0)
	v_lshlrev_b32_e32 v13, 16, v10
	v_and_b32_e32 v10, 0xffff0000, v10
	v_mul_f32_e32 v10, v1, v10
	v_fmac_f32_e32 v10, v0, v13
	v_lshlrev_b32_e32 v13, 16, v11
	v_fmac_f32_e32 v10, v2, v13
	v_and_b32_e32 v11, 0xffff0000, v11
	v_fmac_f32_e32 v10, v3, v11
	s_nop 1
	v_add_f32_dpp v10, v10, v10 quad_perm:[1,0,3,2] row_mask:0xf bank_mask:0xf bound_ctrl:1
	s_nop 1
	v_add_f32_dpp v10, v10, v10 quad_perm:[2,3,0,1] row_mask:0xf bank_mask:0xf bound_ctrl:1
	s_nop 1
	v_add_f32_dpp v10, v10, v10 row_half_mirror row_mask:0xf bank_mask:0xf bound_ctrl:1
	s_nop 1
	v_add_f32_dpp v10, v10, v10 row_mirror row_mask:0xf bank_mask:0xf bound_ctrl:1
	s_nop 0
	v_readlane_b32 s18, v10, 0
	v_readlane_b32 s11, v10, 16
	v_readlane_b32 s19, v10, 32
	v_readlane_b32 s20, v10, 48
	s_and_saveexec_b64 s[6:7], vcc
	v_mov_b32_e32 v10, s11
	v_mov_b32_e32 v11, s20
	v_pk_add_f32 v[10:11], s[18:19], v[10:11]
	s_nop 0
	v_add_f32_e32 v10, v10, v11
	ds_write_b32 v9, v10 offset:10504
	s_or_b64 exec, exec, s[6:7]
	v_mov_b32_e32 v10, v216
	v_mov_b32_e32 v11, v217
	s_waitcnt vmcnt(0)
	v_lshlrev_b32_e32 v13, 16, v10
	v_and_b32_e32 v10, 0xffff0000, v10
	v_mul_f32_e32 v10, v1, v10
	v_fmac_f32_e32 v10, v0, v13
	v_lshlrev_b32_e32 v13, 16, v11
	v_fmac_f32_e32 v10, v2, v13
	v_and_b32_e32 v11, 0xffff0000, v11
	v_fmac_f32_e32 v10, v3, v11
	s_nop 1
	v_add_f32_dpp v10, v10, v10 quad_perm:[1,0,3,2] row_mask:0xf bank_mask:0xf bound_ctrl:1
	s_nop 1
	v_add_f32_dpp v10, v10, v10 quad_perm:[2,3,0,1] row_mask:0xf bank_mask:0xf bound_ctrl:1
	s_nop 1
	v_add_f32_dpp v10, v10, v10 row_half_mirror row_mask:0xf bank_mask:0xf bound_ctrl:1
	s_nop 1
	v_add_f32_dpp v10, v10, v10 row_mirror row_mask:0xf bank_mask:0xf bound_ctrl:1
	s_nop 0
	v_readlane_b32 s18, v10, 0
	v_readlane_b32 s11, v10, 16
	v_readlane_b32 s19, v10, 32
	v_readlane_b32 s20, v10, 48
	s_and_saveexec_b64 s[6:7], vcc
	v_mov_b32_e32 v10, s11
	v_mov_b32_e32 v11, s20
	v_pk_add_f32 v[10:11], s[18:19], v[10:11]
	s_nop 0
	v_add_f32_e32 v10, v10, v11
	ds_write_b32 v9, v10 offset:10508
	s_or_b64 exec, exec, s[6:7]
	v_mov_b32_e32 v10, v218
	v_mov_b32_e32 v11, v219
	s_waitcnt vmcnt(0)
	v_lshlrev_b32_e32 v13, 16, v10
	v_and_b32_e32 v10, 0xffff0000, v10
	v_mul_f32_e32 v10, v1, v10
	v_fmac_f32_e32 v10, v0, v13
	v_lshlrev_b32_e32 v13, 16, v11
	v_fmac_f32_e32 v10, v2, v13
	v_and_b32_e32 v11, 0xffff0000, v11
	v_fmac_f32_e32 v10, v3, v11
	s_nop 1
	v_add_f32_dpp v10, v10, v10 quad_perm:[1,0,3,2] row_mask:0xf bank_mask:0xf bound_ctrl:1
	s_nop 1
	v_add_f32_dpp v10, v10, v10 quad_perm:[2,3,0,1] row_mask:0xf bank_mask:0xf bound_ctrl:1
	s_nop 1
	v_add_f32_dpp v10, v10, v10 row_half_mirror row_mask:0xf bank_mask:0xf bound_ctrl:1
	s_nop 1
	v_add_f32_dpp v10, v10, v10 row_mirror row_mask:0xf bank_mask:0xf bound_ctrl:1
	s_nop 0
	v_readlane_b32 s18, v10, 0
	v_readlane_b32 s11, v10, 16
	v_readlane_b32 s19, v10, 32
	v_readlane_b32 s20, v10, 48
	s_and_saveexec_b64 s[6:7], vcc
	v_mov_b32_e32 v10, s11
	v_mov_b32_e32 v11, s20
	v_pk_add_f32 v[10:11], s[18:19], v[10:11]
	s_nop 0
	v_add_f32_e32 v10, v10, v11
	ds_write_b32 v9, v10 offset:10512
	s_or_b64 exec, exec, s[6:7]
	v_mov_b32_e32 v10, v220
	v_mov_b32_e32 v11, v221
	s_waitcnt vmcnt(0)
	v_lshlrev_b32_e32 v13, 16, v10
	v_and_b32_e32 v10, 0xffff0000, v10
	v_mul_f32_e32 v10, v1, v10
	v_fmac_f32_e32 v10, v0, v13
	v_lshlrev_b32_e32 v13, 16, v11
	v_fmac_f32_e32 v10, v2, v13
	v_and_b32_e32 v11, 0xffff0000, v11
	v_fmac_f32_e32 v10, v3, v11
	s_nop 1
	v_add_f32_dpp v10, v10, v10 quad_perm:[1,0,3,2] row_mask:0xf bank_mask:0xf bound_ctrl:1
	s_nop 1
	v_add_f32_dpp v10, v10, v10 quad_perm:[2,3,0,1] row_mask:0xf bank_mask:0xf bound_ctrl:1
	s_nop 1
	v_add_f32_dpp v10, v10, v10 row_half_mirror row_mask:0xf bank_mask:0xf bound_ctrl:1
	s_nop 1
	v_add_f32_dpp v10, v10, v10 row_mirror row_mask:0xf bank_mask:0xf bound_ctrl:1
	s_nop 0
	v_readlane_b32 s18, v10, 0
	v_readlane_b32 s11, v10, 16
	v_readlane_b32 s19, v10, 32
	v_readlane_b32 s20, v10, 48
	s_and_saveexec_b64 s[6:7], vcc
	v_mov_b32_e32 v10, s11
	v_mov_b32_e32 v11, s20
	v_pk_add_f32 v[10:11], s[18:19], v[10:11]
	s_nop 0
	v_add_f32_e32 v10, v10, v11
	ds_write_b32 v9, v10 offset:10516
	s_or_b64 exec, exec, s[6:7]
	v_mov_b32_e32 v10, v222
	v_mov_b32_e32 v11, v223
	s_waitcnt vmcnt(0)
	v_lshlrev_b32_e32 v13, 16, v10
	v_and_b32_e32 v10, 0xffff0000, v10
	v_mul_f32_e32 v10, v1, v10
	v_fmac_f32_e32 v10, v0, v13
	v_lshlrev_b32_e32 v13, 16, v11
	v_fmac_f32_e32 v10, v2, v13
	v_and_b32_e32 v11, 0xffff0000, v11
	v_fmac_f32_e32 v10, v3, v11
	s_nop 1
	v_add_f32_dpp v10, v10, v10 quad_perm:[1,0,3,2] row_mask:0xf bank_mask:0xf bound_ctrl:1
	s_nop 1
	v_add_f32_dpp v10, v10, v10 quad_perm:[2,3,0,1] row_mask:0xf bank_mask:0xf bound_ctrl:1
	s_nop 1
	v_add_f32_dpp v10, v10, v10 row_half_mirror row_mask:0xf bank_mask:0xf bound_ctrl:1
	s_nop 1
	v_add_f32_dpp v10, v10, v10 row_mirror row_mask:0xf bank_mask:0xf bound_ctrl:1
	s_nop 0
	v_readlane_b32 s18, v10, 0
	v_readlane_b32 s11, v10, 16
	v_readlane_b32 s19, v10, 32
	v_readlane_b32 s20, v10, 48
	s_and_saveexec_b64 s[6:7], vcc
	v_mov_b32_e32 v10, s11
	v_mov_b32_e32 v11, s20
	v_pk_add_f32 v[10:11], s[18:19], v[10:11]
	s_nop 0
	v_add_f32_e32 v10, v10, v11
	ds_write_b32 v9, v10 offset:10520
	s_or_b64 exec, exec, s[6:7]
	v_mov_b32_e32 v4, v224
	v_mov_b32_e32 v5, v225
	s_waitcnt vmcnt(0)
	v_lshlrev_b32_e32 v6, 16, v4
	v_and_b32_e32 v4, 0xffff0000, v4
	v_mul_f32_e32 v1, v1, v4
	v_lshlrev_b32_e32 v7, 16, v5
	v_fmac_f32_e32 v1, v0, v6
	v_and_b32_e32 v5, 0xffff0000, v5
	v_fmac_f32_e32 v1, v2, v7
	v_fmac_f32_e32 v1, v3, v5
	s_nop 1
	v_add_f32_dpp v0, v1, v1 quad_perm:[1,0,3,2] row_mask:0xf bank_mask:0xf bound_ctrl:1
	s_nop 1
	v_add_f32_dpp v0, v0, v0 quad_perm:[2,3,0,1] row_mask:0xf bank_mask:0xf bound_ctrl:1
	s_nop 1
	v_add_f32_dpp v0, v0, v0 row_half_mirror row_mask:0xf bank_mask:0xf bound_ctrl:1
	s_nop 1
	v_add_f32_dpp v0, v0, v0 row_mirror row_mask:0xf bank_mask:0xf bound_ctrl:1
	s_nop 0
	v_readlane_b32 s18, v0, 0
	v_readlane_b32 s11, v0, 16
	v_readlane_b32 s19, v0, 32
	v_readlane_b32 s20, v0, 48
	s_and_saveexec_b64 s[6:7], vcc
	v_mov_b32_e32 v0, s11
	v_mov_b32_e32 v1, s20
	v_pk_add_f32 v[0:1], s[18:19], v[0:1]
	s_nop 0
	v_add_f32_e32 v0, v0, v1
	ds_write_b32 v9, v0 offset:10524
	s_or_b64 exec, exec, s[6:7]
	v_lshlrev_b32_e32 v2, 1, v12
	v_lshlrev_b32_e32 v1, 8, v33
	v_and_b32_e32 v2, 32, v2
	s_add_u32 s4, s4, s16
	v_or3_b32 v1, v2, v1, v63
	s_addc_u32 s5, s5, s17
	v_and_b32_e32 v7, 0x200, v8
	v_lshlrev_b32_e32 v50, 3, v1
	s_add_u32 s4, s4, 0x2c240000
	v_or_b32_e32 v30, v50, v7
	v_or_b32_e32 v56, 0x80, v50
	s_addc_u32 s5, s5, 0
	v_ashrrev_i32_e32 v31, 31, v30
	v_or_b32_e32 v54, v56, v7
	v_mov_b32_e32 v0, v169
	v_mov_b32_e32 v4, v169
	v_mov_b32_e32 v10, v169
	v_mov_b32_e32 v14, v169
	v_lshl_add_u64 v[2:3], v[30:31], 1, s[4:5]
	v_ashrrev_i32_e32 v55, 31, v54
	global_load_dwordx4 v[18:21], v[2:3], off
	v_lshl_add_u64 v[2:3], v[54:55], 1, s[4:5]
	global_load_dwordx4 v[22:25], v[2:3], off
	v_and_b32_e32 v5, 48, v32
	v_mul_u32_u24_e32 v6, 0x90, v63
	v_add3_u32 v58, 0, v5, v6
	ds_read_b128 v[6:9], v58
	ds_read_b128 v[34:37], v58 offset:2304
	v_mov_b32_e32 v1, v0
	v_mov_b32_e32 v2, v0
	v_mov_b32_e32 v3, v0
	v_mov_b32_e32 v5, v4
	v_mov_b32_e32 v11, v10
	v_mov_b32_e32 v12, v10
	v_mov_b32_e32 v13, v10
	v_ashrrev_i32_e32 v31, 31, v50
	v_ashrrev_i32_e32 v55, 31, v56
	v_mov_b32_e32 v15, v14
	v_mov_b32_e32 v16, v14
	v_mov_b32_e32 v17, v14
	s_lshl_b32 s6, s2, 8
	s_ashr_i32 s7, s6, 31
	v_mov_b32_e32 v59, v169
	v_and_b32_e32 v32, 0x3fffffc0, v32
	v_lshl_add_u32 v62, v66, 2, 0
	v_cmp_eq_u32_e32 vcc, 0, v63
	s_waitcnt vmcnt(1) lgkmcnt(1)
	v_mfma_f32_16x16x32_bf16 v[26:29], v[6:9], v[18:21], v[0:3]
	s_waitcnt vmcnt(0)
	v_mfma_f32_16x16x32_bf16 v[0:3], v[6:9], v[22:25], v[0:3]
	v_mov_b32_e32 v6, v4
	v_mov_b32_e32 v7, v4
	s_waitcnt lgkmcnt(0)
	s_nop 0
	v_mfma_f32_16x16x32_bf16 v[38:41], v[34:37], v[18:21], v[4:7]
	v_mfma_f32_16x16x32_bf16 v[4:7], v[34:37], v[22:25], v[4:7]
	ds_read_b128 v[34:37], v58 offset:4608
	s_waitcnt lgkmcnt(0)
	v_mfma_f32_16x16x32_bf16 v[42:45], v[34:37], v[18:21], v[10:13]
	v_mfma_f32_16x16x32_bf16 v[8:11], v[34:37], v[22:25], v[10:13]
	ds_read_b128 v[34:37], v58 offset:6912
	s_nop 1
	v_lshl_add_u64 v[12:13], v[30:31], 1, s[4:5]
	global_load_dwordx4 v[50:53], v[12:13], off offset:2048
	v_lshl_add_u64 v[12:13], v[54:55], 1, s[4:5]
	global_load_dwordx4 v[54:57], v[12:13], off offset:2048
	s_waitcnt lgkmcnt(0)
	v_mfma_f32_16x16x32_bf16 v[46:49], v[34:37], v[18:21], v[14:17]
	s_lshl_b64 s[4:5], s[6:7], 2
	s_add_u32 s14, s14, s4
	s_addc_u32 s15, s15, s5
	v_mfma_f32_16x16x32_bf16 v[34:37], v[34:37], v[22:25], v[14:17]
	s_nop 2
	ds_read_b128 v[12:15], v58 offset:64
	s_waitcnt vmcnt(1) lgkmcnt(0)
	v_mfma_f32_16x16x32_bf16 v[28:31], v[12:15], v[50:53], v[26:29]
	s_waitcnt vmcnt(0)
	v_mfma_f32_16x16x32_bf16 v[24:27], v[12:15], v[54:57], v[0:3]
	s_nop 2
	ds_read_b128 v[0:3], v58 offset:2368
	s_waitcnt lgkmcnt(0)
	v_mfma_f32_16x16x32_bf16 v[20:23], v[0:3], v[50:53], v[38:41]
	s_nop 2
	v_lshl_add_u32 v40, v32, 2, 0
	v_mov_b32_e32 v39, v169
	v_mfma_f32_16x16x32_bf16 v[16:19], v[0:3], v[54:57], v[4:7]
	ds_read_b128 v[0:3], v58 offset:4672
	s_nop 1
	ds_read_b128 v[4:7], v58 offset:6976
	s_waitcnt lgkmcnt(1)
	v_mfma_f32_16x16x32_bf16 v[12:15], v[0:3], v[50:53], v[42:45]
	v_lshlrev_b32_e32 v58, 2, v63
	s_waitcnt lgkmcnt(0)
	s_barrier
	v_mfma_f32_16x16x32_bf16 v[8:11], v[0:3], v[54:57], v[8:11]
	v_mfma_f32_16x16x32_bf16 v[0:3], v[4:7], v[50:53], v[46:49]
	v_mfma_f32_16x16x32_bf16 v[4:7], v[4:7], v[54:57], v[34:37]
	s_nop 2
	v_lshlrev_b32_e32 v36, 5, v33
	v_ashrrev_i32_e32 v37, 31, v36
	v_lshl_add_u64 v[34:35], v[36:37], 2, s[14:15]
	v_lshl_add_u64 v[34:35], v[34:35], 0, v[58:59]
	s_mov_b64 s[14:15], 0x9640000
	v_lshl_add_u64 v[60:61], v[34:35], 0, s[14:15]
	v_or_b32_e32 v210, s24, v66
	v_lshlrev_b32_e32 v208, 12, v210
	v_mov_b32_e32 v209, v169
	s_mov_b64 s[26:27], 0x1000
	v_lshl_add_u64 v[208:209], v[60:61], 0, v[208:209]
	global_load_dword v176, v[208:209], off
	global_load_dword v177, v[208:209], off offset:64
	v_lshl_add_u64 v[210:211], v[208:209], 0, s[26:27]
	global_load_dword v178, v[210:211], off
	global_load_dword v179, v[210:211], off offset:64
	v_lshl_add_u64 v[210:211], v[210:211], 0, s[26:27]
	global_load_dword v180, v[210:211], off
	global_load_dword v181, v[210:211], off offset:64
	v_lshl_add_u64 v[210:211], v[210:211], 0, s[26:27]
	global_load_dword v182, v[210:211], off
	global_load_dword v183, v[210:211], off offset:64
	s_mov_b64 s[26:27], 0x10000
	v_lshl_add_u64 v[208:209], v[208:209], 0, s[26:27]
	s_mov_b64 s[26:27], 0x1000
	global_load_dword v184, v[208:209], off
	global_load_dword v185, v[208:209], off offset:64
	v_lshl_add_u64 v[210:211], v[208:209], 0, s[26:27]
	global_load_dword v186, v[210:211], off
	global_load_dword v187, v[210:211], off offset:64
	v_lshl_add_u64 v[210:211], v[210:211], 0, s[26:27]
	global_load_dword v188, v[210:211], off
	global_load_dword v189, v[210:211], off offset:64
	v_lshl_add_u64 v[210:211], v[210:211], 0, s[26:27]
	global_load_dword v190, v[210:211], off
	global_load_dword v191, v[210:211], off offset:64
	s_mov_b64 s[26:27], 0x10000
	v_lshl_add_u64 v[208:209], v[208:209], 0, s[26:27]
	s_mov_b64 s[26:27], 0x1000
	global_load_dword v192, v[208:209], off
	global_load_dword v193, v[208:209], off offset:64
	v_lshl_add_u64 v[210:211], v[208:209], 0, s[26:27]
	global_load_dword v194, v[210:211], off
	global_load_dword v195, v[210:211], off offset:64
	v_lshl_add_u64 v[210:211], v[210:211], 0, s[26:27]
	global_load_dword v196, v[210:211], off
	global_load_dword v197, v[210:211], off offset:64
	v_lshl_add_u64 v[210:211], v[210:211], 0, s[26:27]
	global_load_dword v198, v[210:211], off
	global_load_dword v199, v[210:211], off offset:64
	s_mov_b64 s[26:27], 0x10000
	v_lshl_add_u64 v[208:209], v[208:209], 0, s[26:27]
	s_mov_b64 s[26:27], 0x1000
	global_load_dword v200, v[208:209], off
	global_load_dword v201, v[208:209], off offset:64
	v_lshl_add_u64 v[210:211], v[208:209], 0, s[26:27]
	global_load_dword v202, v[210:211], off
	global_load_dword v203, v[210:211], off offset:64
	v_lshl_add_u64 v[210:211], v[210:211], 0, s[26:27]
	global_load_dword v204, v[210:211], off
	global_load_dword v205, v[210:211], off offset:64
	v_lshl_add_u64 v[210:211], v[210:211], 0, s[26:27]
	global_load_dword v206, v[210:211], off
	global_load_dword v207, v[210:211], off offset:64
	ds_read2st64_b32 v[32:33], v62 offset0:38 offset1:39
	ds_read2st64_b32 v[34:35], v62 offset0:40 offset1:41
	v_or_b32_e32 v59, s24, v66
	v_lshlrev_b32_e32 v38, 12, v59
	s_waitcnt lgkmcnt(1)
	v_mul_f32_e32 v32, 0xbfb8aa3b, v32
	v_exp_f32_e32 v32, v32
	s_waitcnt lgkmcnt(0)
	v_fmac_f32_e32 v34, v33, v35
	v_max_f32_e64 v32, |v34|, v32
	v_lshl_add_u64 v[34:35], v[60:61], 0, v[38:39]
	s_waitcnt vmcnt(0)
	v_mov_b32_e32 v39, v176
	v_rcp_f32_e32 v32, v32
	s_waitcnt vmcnt(0)
	v_fma_f32 v28, v33, v39, v28
	v_mul_f32_e32 v88, v28, v32
	v_mov_b32_e32 v28, v177
	v_lshl_add_u32 v39, v66, 2, v40
	s_waitcnt vmcnt(0)
	v_fma_f32 v24, v33, v28, v24
	v_mul_f32_e32 v90, v24, v32
	v_mul_f32_e32 v24, v90, v90
	v_fmac_f32_e32 v24, v88, v88
	s_nop 1
	v_add_f32_dpp v24, v24, v24 quad_perm:[1,0,3,2] row_mask:0xf bank_mask:0xf bound_ctrl:1
	s_nop 1
	v_add_f32_dpp v24, v24, v24 quad_perm:[2,3,0,1] row_mask:0xf bank_mask:0xf bound_ctrl:1
	s_nop 1
	v_add_f32_dpp v24, v24, v24 row_half_mirror row_mask:0xf bank_mask:0xf bound_ctrl:1
	s_nop 1
	v_mov_b32_dpp v28, v24 row_mirror row_mask:0xf bank_mask:0xf bound_ctrl:1
	s_and_saveexec_b64 s[14:15], vcc
	v_add_f32_e32 v24, v24, v28
	ds_write_b32 v39, v24 offset:10752
	s_or_b64 exec, exec, s[14:15]
	v_add_u32_e32 v24, 4, v62
	ds_read2st64_b32 v[32:33], v24 offset0:38 offset1:39
	ds_read2st64_b32 v[34:35], v24 offset0:40 offset1:41
	v_or3_b32 v28, v66, s24, 1
	v_lshlrev_b32_e32 v56, 12, v28
	v_mov_b32_e32 v57, v169
	s_waitcnt lgkmcnt(1)
	v_mul_f32_e32 v24, 0xbfb8aa3b, v32
	v_exp_f32_e32 v24, v24
	s_waitcnt lgkmcnt(0)
	v_fmac_f32_e32 v34, v33, v35
	v_max_f32_e64 v24, |v34|, v24
	v_lshl_add_u64 v[34:35], v[60:61], 0, v[56:57]
	v_mov_b32_e32 v28, v178
	v_rcp_f32_e32 v24, v24
	s_waitcnt vmcnt(0)
	v_fma_f32 v28, v33, v28, v29
	v_mul_f32_e32 v89, v28, v24
	v_mov_b32_e32 v28, v179
	s_waitcnt vmcnt(0)
	v_fma_f32 v25, v33, v28, v25
	v_mul_f32_e32 v91, v25, v24
	v_mul_f32_e32 v24, v91, v91
	v_fmac_f32_e32 v24, v89, v89
	s_nop 1
	v_add_f32_dpp v24, v24, v24 quad_perm:[1,0,3,2] row_mask:0xf bank_mask:0xf bound_ctrl:1
	s_nop 1
	v_add_f32_dpp v24, v24, v24 quad_perm:[2,3,0,1] row_mask:0xf bank_mask:0xf bound_ctrl:1
	s_nop 1
	v_add_f32_dpp v24, v24, v24 row_half_mirror row_mask:0xf bank_mask:0xf bound_ctrl:1
	s_nop 1
	v_mov_b32_dpp v25, v24 row_mirror row_mask:0xf bank_mask:0xf bound_ctrl:1
	s_and_saveexec_b64 s[14:15], vcc
	v_add_f32_e32 v24, v24, v25
	ds_write_b32 v39, v24 offset:10756
	s_or_b64 exec, exec, s[14:15]
	v_add_u32_e32 v24, 8, v62
	ds_read2st64_b32 v[28:29], v24 offset0:38 offset1:39
	ds_read2st64_b32 v[24:25], v24 offset0:40 offset1:41
	s_waitcnt lgkmcnt(0)
	v_fmac_f32_e32 v24, v29, v25
	v_mul_f32_e32 v25, 0xbfb8aa3b, v28
	v_exp_f32_e32 v25, v25
	s_nop 0
	v_max_f32_e64 v24, |v24|, v25
	v_rcp_f32_e32 v28, v24
	v_or3_b32 v24, v66, s24, 2
	v_lshlrev_b32_e32 v24, 12, v24
	v_mov_b32_e32 v25, v169
	v_lshl_add_u64 v[32:33], v[60:61], 0, v[24:25]
	v_mov_b32_e32 v25, v180
	s_waitcnt vmcnt(0)
	v_fma_f32 v25, v29, v25, v30
	v_mul_f32_e32 v30, v25, v28
	v_mov_b32_e32 v25, v181
	s_waitcnt vmcnt(0)
	v_fma_f32 v25, v29, v25, v26
	v_mul_f32_e32 v92, v25, v28
	v_mul_f32_e32 v25, v92, v92
	v_fmac_f32_e32 v25, v30, v30
	s_nop 1
	v_add_f32_dpp v25, v25, v25 quad_perm:[1,0,3,2] row_mask:0xf bank_mask:0xf bound_ctrl:1
	s_nop 1
	v_add_f32_dpp v25, v25, v25 quad_perm:[2,3,0,1] row_mask:0xf bank_mask:0xf bound_ctrl:1
	s_nop 1
	v_add_f32_dpp v25, v25, v25 row_half_mirror row_mask:0xf bank_mask:0xf bound_ctrl:1
	s_nop 1
	v_mov_b32_dpp v26, v25 row_mirror row_mask:0xf bank_mask:0xf bound_ctrl:1
	s_and_saveexec_b64 s[14:15], vcc
	v_add_f32_e32 v25, v25, v26
	ds_write_b32 v39, v25 offset:10760
	s_or_b64 exec, exec, s[14:15]
	v_add_u32_e32 v25, 12, v62
	ds_read2st64_b32 v[32:33], v25 offset0:38 offset1:39
	ds_read2st64_b32 v[28:29], v25 offset0:40 offset1:41
	v_or3_b32 v26, v66, s24, 3
	s_waitcnt lgkmcnt(1)
	v_mul_f32_e32 v25, 0xbfb8aa3b, v32
	v_exp_f32_e32 v25, v25
	s_waitcnt lgkmcnt(0)
	v_fmac_f32_e32 v28, v33, v29
	v_mov_b32_e32 v29, v169
	v_max_f32_e64 v25, |v28|, v25
	v_lshlrev_b32_e32 v28, 12, v26
	v_lshl_add_u64 v[34:35], v[60:61], 0, v[28:29]
	v_mov_b32_e32 v26, v182
	v_rcp_f32_e32 v25, v25
	s_waitcnt vmcnt(0)
	v_fmac_f32_e32 v31, v33, v26
	v_mov_b32_e32 v26, v183
	v_mul_f32_e32 v31, v31, v25
	s_waitcnt vmcnt(0)
	v_fmac_f32_e32 v27, v33, v26
	v_mul_f32_e32 v93, v27, v25
	v_mul_f32_e32 v25, v93, v93
	v_fmac_f32_e32 v25, v31, v31
	s_nop 1
	v_add_f32_dpp v25, v25, v25 quad_perm:[1,0,3,2] row_mask:0xf bank_mask:0xf bound_ctrl:1
	s_nop 1
	v_add_f32_dpp v25, v25, v25 quad_perm:[2,3,0,1] row_mask:0xf bank_mask:0xf bound_ctrl:1
	s_nop 1
	v_add_f32_dpp v25, v25, v25 row_half_mirror row_mask:0xf bank_mask:0xf bound_ctrl:1
	s_nop 1
	v_mov_b32_dpp v26, v25 row_mirror row_mask:0xf bank_mask:0xf bound_ctrl:1
	s_and_saveexec_b64 s[14:15], vcc
	v_add_f32_e32 v25, v25, v26
	ds_write_b32 v39, v25 offset:10764
	s_or_b64 exec, exec, s[14:15]
	v_add_u32_e32 v25, 64, v62
	ds_read2st64_b32 v[32:33], v25 offset0:38 offset1:39
	ds_read2st64_b32 v[26:27], v25 offset0:40 offset1:41
	s_waitcnt lgkmcnt(1)
	v_mul_f32_e32 v25, 0xbfb8aa3b, v32
	v_exp_f32_e32 v25, v25
	s_waitcnt lgkmcnt(0)
	v_fmac_f32_e32 v26, v33, v27
	v_mov_b32_e32 v27, v169
	v_max_f32_e64 v25, |v26|, v25
	v_or3_b32 v26, v66, s24, 16
	v_lshlrev_b32_e32 v26, 12, v26
	v_lshl_add_u64 v[34:35], v[60:61], 0, v[26:27]
	v_mov_b32_e32 v27, v184
	v_rcp_f32_e32 v25, v25
	s_waitcnt vmcnt(0)
	v_fma_f32 v20, v33, v27, v20
	v_mov_b32_e32 v27, v185
	v_mul_f32_e32 v20, v20, v25
	s_waitcnt vmcnt(0)
	v_fma_f32 v16, v33, v27, v16
	v_mul_f32_e32 v16, v16, v25
	v_mul_f32_e32 v25, v16, v16
	v_fmac_f32_e32 v25, v20, v20
	s_nop 1
	v_add_f32_dpp v25, v25, v25 quad_perm:[1,0,3,2] row_mask:0xf bank_mask:0xf bound_ctrl:1
	s_nop 1
	v_add_f32_dpp v25, v25, v25 quad_perm:[2,3,0,1] row_mask:0xf bank_mask:0xf bound_ctrl:1
	s_nop 1
	v_add_f32_dpp v25, v25, v25 row_half_mirror row_mask:0xf bank_mask:0xf bound_ctrl:1
	s_nop 1
	v_mov_b32_dpp v27, v25 row_mirror row_mask:0xf bank_mask:0xf bound_ctrl:1
	s_and_saveexec_b64 s[14:15], vcc
	v_add_f32_e32 v25, v25, v27
	ds_write_b32 v39, v25 offset:10816
	s_or_b64 exec, exec, s[14:15]
	v_add_u32_e32 v25, 0x44, v62
	ds_read2st64_b32 v[32:33], v25 offset0:38 offset1:39
	ds_read2st64_b32 v[34:35], v25 offset0:40 offset1:41
	v_or3_b32 v27, v66, s24, 17
	v_lshlrev_b32_e32 v40, 12, v27
	v_mov_b32_e32 v41, v169
	s_waitcnt lgkmcnt(1)
	v_mul_f32_e32 v25, 0xbfb8aa3b, v32
	v_exp_f32_e32 v25, v25
	s_waitcnt lgkmcnt(0)
	v_fmac_f32_e32 v34, v33, v35
	v_max_f32_e64 v25, |v34|, v25
	v_lshl_add_u64 v[34:35], v[60:61], 0, v[40:41]
	v_mov_b32_e32 v27, v186
	v_rcp_f32_e32 v25, v25
	s_waitcnt vmcnt(0)
	v_fma_f32 v21, v33, v27, v21
	v_mul_f32_e32 v73, v21, v25
	v_mov_b32_e32 v21, v187
	s_waitcnt vmcnt(0)
	v_fma_f32 v17, v33, v21, v17
	v_mul_f32_e32 v72, v17, v25
	v_mul_f32_e32 v17, v72, v72
	v_fmac_f32_e32 v17, v73, v73
	s_nop 1
	v_add_f32_dpp v17, v17, v17 quad_perm:[1,0,3,2] row_mask:0xf bank_mask:0xf bound_ctrl:1
	s_nop 1
	v_add_f32_dpp v17, v17, v17 quad_perm:[2,3,0,1] row_mask:0xf bank_mask:0xf bound_ctrl:1
	s_nop 1
	v_add_f32_dpp v17, v17, v17 row_half_mirror row_mask:0xf bank_mask:0xf bound_ctrl:1
	s_nop 1
	v_mov_b32_dpp v21, v17 row_mirror row_mask:0xf bank_mask:0xf bound_ctrl:1
	s_and_saveexec_b64 s[14:15], vcc
	v_add_f32_e32 v17, v17, v21
	ds_write_b32 v39, v17 offset:10820
	s_or_b64 exec, exec, s[14:15]
	v_add_u32_e32 v17, 0x48, v62
	ds_read2st64_b32 v[32:33], v17 offset0:38 offset1:39
	ds_read2st64_b32 v[34:35], v17 offset0:40 offset1:41
	v_or3_b32 v21, v66, s24, 18
	v_lshlrev_b32_e32 v42, 12, v21
	v_mov_b32_e32 v43, v169
	s_waitcnt lgkmcnt(1)
	v_mul_f32_e32 v17, 0xbfb8aa3b, v32
	v_exp_f32_e32 v17, v17
	s_waitcnt lgkmcnt(0)
	v_fmac_f32_e32 v34, v33, v35
	v_max_f32_e64 v17, |v34|, v17
	v_lshl_add_u64 v[34:35], v[60:61], 0, v[42:43]
	v_mov_b32_e32 v21, v188
	v_rcp_f32_e32 v17, v17
	s_waitcnt vmcnt(0)
	v_fma_f32 v21, v33, v21, v22
	v_mul_f32_e32 v76, v21, v17
	v_mov_b32_e32 v21, v189
	s_waitcnt vmcnt(0)
	v_fma_f32 v18, v33, v21, v18
	v_mul_f32_e32 v77, v18, v17
	v_mul_f32_e32 v17, v77, v77
	v_fmac_f32_e32 v17, v76, v76
	s_nop 1
	v_add_f32_dpp v17, v17, v17 quad_perm:[1,0,3,2] row_mask:0xf bank_mask:0xf bound_ctrl:1
	s_nop 1
	v_add_f32_dpp v17, v17, v17 quad_perm:[2,3,0,1] row_mask:0xf bank_mask:0xf bound_ctrl:1
	s_nop 1
	v_add_f32_dpp v17, v17, v17 row_half_mirror row_mask:0xf bank_mask:0xf bound_ctrl:1
	s_nop 1
	v_mov_b32_dpp v18, v17 row_mirror row_mask:0xf bank_mask:0xf bound_ctrl:1
	s_and_saveexec_b64 s[14:15], vcc
	v_add_f32_e32 v17, v17, v18
	ds_write_b32 v39, v17 offset:10824
	s_or_b64 exec, exec, s[14:15]
	v_add_u32_e32 v17, 0x4c, v62
	ds_read2st64_b32 v[32:33], v17 offset0:38 offset1:39
	ds_read2st64_b32 v[34:35], v17 offset0:40 offset1:41
	v_or3_b32 v18, v66, s24, 19
	v_lshlrev_b32_e32 v44, 12, v18
	v_mov_b32_e32 v45, v169
	s_waitcnt lgkmcnt(1)
	v_mul_f32_e32 v17, 0xbfb8aa3b, v32
	v_exp_f32_e32 v17, v17
	s_waitcnt lgkmcnt(0)
	v_fmac_f32_e32 v34, v33, v35
	v_max_f32_e64 v17, |v34|, v17
	v_lshl_add_u64 v[34:35], v[60:61], 0, v[44:45]
	v_mov_b32_e32 v18, v190
	v_rcp_f32_e32 v17, v17
	s_waitcnt vmcnt(0)
	v_fmac_f32_e32 v23, v33, v18
	v_mov_b32_e32 v18, v191
	v_mul_f32_e32 v75, v23, v17
	s_waitcnt vmcnt(0)
	v_fmac_f32_e32 v19, v33, v18
	v_mul_f32_e32 v74, v19, v17
	v_mul_f32_e32 v17, v74, v74
	v_fmac_f32_e32 v17, v75, v75
	s_nop 1
	v_add_f32_dpp v17, v17, v17 quad_perm:[1,0,3,2] row_mask:0xf bank_mask:0xf bound_ctrl:1
	s_nop 1
	v_add_f32_dpp v17, v17, v17 quad_perm:[2,3,0,1] row_mask:0xf bank_mask:0xf bound_ctrl:1
	s_nop 1
	v_add_f32_dpp v17, v17, v17 row_half_mirror row_mask:0xf bank_mask:0xf bound_ctrl:1
	s_nop 1
	v_mov_b32_dpp v18, v17 row_mirror row_mask:0xf bank_mask:0xf bound_ctrl:1
	s_and_saveexec_b64 s[14:15], vcc
	v_add_f32_e32 v17, v17, v18
	ds_write_b32 v39, v17 offset:10828
	s_or_b64 exec, exec, s[14:15]
	v_add_u32_e32 v17, 0x80, v62
	ds_read2st64_b32 v[18:19], v17 offset0:38 offset1:39
	ds_read2st64_b32 v[22:23], v17 offset0:40 offset1:41
	v_mov_b32_e32 v47, v169
	s_waitcnt lgkmcnt(1)
	v_mul_f32_e32 v17, 0xbfb8aa3b, v18
	v_exp_f32_e32 v17, v17
	v_or3_b32 v18, v66, s24, 32
	s_waitcnt lgkmcnt(0)
	v_fmac_f32_e32 v22, v19, v23
	v_lshlrev_b32_e32 v46, 12, v18
	v_max_f32_e64 v17, |v22|, v17
	v_lshl_add_u64 v[22:23], v[60:61], 0, v[46:47]
	v_mov_b32_e32 v18, v192
	v_rcp_f32_e32 v17, v17
	s_waitcnt vmcnt(0)
	v_fma_f32 v12, v19, v18, v12
	v_mul_f32_e32 v78, v12, v17
	v_mov_b32_e32 v12, v193
	s_waitcnt vmcnt(0)
	v_fma_f32 v8, v19, v12, v8
	v_mul_f32_e32 v80, v8, v17
	v_mul_f32_e32 v8, v80, v80
	v_fmac_f32_e32 v8, v78, v78
	s_nop 1
	v_add_f32_dpp v8, v8, v8 quad_perm:[1,0,3,2] row_mask:0xf bank_mask:0xf bound_ctrl:1
	s_nop 1
	v_add_f32_dpp v8, v8, v8 quad_perm:[2,3,0,1] row_mask:0xf bank_mask:0xf bound_ctrl:1
	s_nop 1
	v_add_f32_dpp v8, v8, v8 row_half_mirror row_mask:0xf bank_mask:0xf bound_ctrl:1
	s_nop 1
	v_mov_b32_dpp v12, v8 row_mirror row_mask:0xf bank_mask:0xf bound_ctrl:1
	s_and_saveexec_b64 s[14:15], vcc
	v_add_f32_e32 v8, v8, v12
	ds_write_b32 v39, v8 offset:10880
	s_or_b64 exec, exec, s[14:15]
	v_add_u32_e32 v8, 0x84, v62
	ds_read2st64_b32 v[18:19], v8 offset0:38 offset1:39
	ds_read2st64_b32 v[22:23], v8 offset0:40 offset1:41
	v_or3_b32 v12, v66, s24, 33
	v_lshlrev_b32_e32 v48, 12, v12
	v_mov_b32_e32 v49, v169
	s_waitcnt lgkmcnt(1)
	v_mul_f32_e32 v8, 0xbfb8aa3b, v18
	v_exp_f32_e32 v8, v8
	s_waitcnt lgkmcnt(0)
	v_fmac_f32_e32 v22, v19, v23
	v_max_f32_e64 v8, |v22|, v8
	v_lshl_add_u64 v[22:23], v[60:61], 0, v[48:49]
	v_mov_b32_e32 v12, v194
	v_rcp_f32_e32 v8, v8
	s_waitcnt vmcnt(0)
	v_fma_f32 v12, v19, v12, v13
	v_mul_f32_e32 v79, v12, v8
	v_mov_b32_e32 v12, v195
	s_waitcnt vmcnt(0)
	v_fma_f32 v9, v19, v12, v9
	v_mul_f32_e32 v81, v9, v8
	v_mul_f32_e32 v8, v81, v81
	v_fmac_f32_e32 v8, v79, v79
	s_nop 1
	v_add_f32_dpp v8, v8, v8 quad_perm:[1,0,3,2] row_mask:0xf bank_mask:0xf bound_ctrl:1
	s_nop 1
	v_add_f32_dpp v8, v8, v8 quad_perm:[2,3,0,1] row_mask:0xf bank_mask:0xf bound_ctrl:1
	s_nop 1
	v_add_f32_dpp v8, v8, v8 row_half_mirror row_mask:0xf bank_mask:0xf bound_ctrl:1
	s_nop 1
	v_mov_b32_dpp v9, v8 row_mirror row_mask:0xf bank_mask:0xf bound_ctrl:1
	s_and_saveexec_b64 s[14:15], vcc
	v_add_f32_e32 v8, v8, v9
	ds_write_b32 v39, v8 offset:10884
	s_or_b64 exec, exec, s[14:15]
	v_add_u32_e32 v12, 0x88, v62
	ds_read2st64_b32 v[8:9], v12 offset0:38 offset1:39
	ds_read2st64_b32 v[12:13], v12 offset0:40 offset1:41
	v_mov_b32_e32 v51, v169
	s_waitcnt lgkmcnt(1)
	v_mul_f32_e32 v8, 0xbfb8aa3b, v8
	v_exp_f32_e32 v8, v8
	s_waitcnt lgkmcnt(0)
	v_fmac_f32_e32 v12, v9, v13
	v_max_f32_e64 v8, |v12|, v8
	v_or3_b32 v12, v66, s24, 34
	v_lshlrev_b32_e32 v50, 12, v12
	v_lshl_add_u64 v[12:13], v[60:61], 0, v[50:51]
	v_mov_b32_e32 v17, v196
	v_rcp_f32_e32 v8, v8
	v_mov_b32_e32 v12, v197
	s_waitcnt vmcnt(1)
	v_fma_f32 v14, v9, v17, v14
	v_mul_f32_e32 v82, v14, v8
	s_waitcnt vmcnt(0)
	v_fma_f32 v9, v9, v12, v10
	v_mul_f32_e32 v83, v9, v8
	v_mul_f32_e32 v8, v83, v83
	v_fmac_f32_e32 v8, v82, v82
	s_nop 1
	v_add_f32_dpp v8, v8, v8 quad_perm:[1,0,3,2] row_mask:0xf bank_mask:0xf bound_ctrl:1
	s_nop 1
	v_add_f32_dpp v8, v8, v8 quad_perm:[2,3,0,1] row_mask:0xf bank_mask:0xf bound_ctrl:1
	s_nop 1
	v_add_f32_dpp v8, v8, v8 row_half_mirror row_mask:0xf bank_mask:0xf bound_ctrl:1
	s_nop 1
	v_mov_b32_dpp v9, v8 row_mirror row_mask:0xf bank_mask:0xf bound_ctrl:1
	s_and_saveexec_b64 s[14:15], vcc
	v_add_f32_e32 v8, v8, v9
	ds_write_b32 v39, v8 offset:10888
	s_or_b64 exec, exec, s[14:15]
	v_add_u32_e32 v10, 0x8c, v62
	ds_read2st64_b32 v[8:9], v10 offset0:38 offset1:39
	ds_read2st64_b32 v[12:13], v10 offset0:40 offset1:41
	v_or3_b32 v10, v66, s24, 35
	v_lshlrev_b32_e32 v52, 12, v10
	v_mov_b32_e32 v53, v169
	s_waitcnt lgkmcnt(1)
	v_mul_f32_e32 v8, 0xbfb8aa3b, v8
	v_exp_f32_e32 v8, v8
	s_waitcnt lgkmcnt(0)
	v_fmac_f32_e32 v12, v9, v13
	v_max_f32_e64 v8, |v12|, v8
	v_lshl_add_u64 v[12:13], v[60:61], 0, v[52:53]
	v_mov_b32_e32 v10, v198
	v_rcp_f32_e32 v8, v8
	s_waitcnt vmcnt(0)
	v_fmac_f32_e32 v15, v9, v10
	v_mov_b32_e32 v10, v199
	v_mul_f32_e32 v84, v15, v8
	s_waitcnt vmcnt(0)
	v_fmac_f32_e32 v11, v9, v10
	v_mul_f32_e32 v85, v11, v8
	v_mul_f32_e32 v8, v85, v85
	v_fmac_f32_e32 v8, v84, v84
	s_nop 1
	v_add_f32_dpp v8, v8, v8 quad_perm:[1,0,3,2] row_mask:0xf bank_mask:0xf bound_ctrl:1
	s_nop 1
	v_add_f32_dpp v8, v8, v8 quad_perm:[2,3,0,1] row_mask:0xf bank_mask:0xf bound_ctrl:1
	s_nop 1
	v_add_f32_dpp v8, v8, v8 row_half_mirror row_mask:0xf bank_mask:0xf bound_ctrl:1
	s_nop 1
	v_mov_b32_dpp v9, v8 row_mirror row_mask:0xf bank_mask:0xf bound_ctrl:1
	s_and_saveexec_b64 s[14:15], vcc
	v_add_f32_e32 v8, v8, v9
	ds_write_b32 v39, v8 offset:10892
	s_or_b64 exec, exec, s[14:15]
	v_add_u32_e32 v10, 0xc0, v62
	ds_read2st64_b32 v[8:9], v10 offset0:38 offset1:39
	ds_read2st64_b32 v[10:11], v10 offset0:40 offset1:41
	v_mov_b32_e32 v55, v169
	s_waitcnt lgkmcnt(1)
	v_mul_f32_e32 v8, 0xbfb8aa3b, v8
	v_exp_f32_e32 v8, v8
	s_waitcnt lgkmcnt(0)
	v_fmac_f32_e32 v10, v9, v11
	v_max_f32_e64 v8, |v10|, v8
	v_or3_b32 v10, v66, s24, 48
	v_lshlrev_b32_e32 v54, 12, v10
	v_lshl_add_u64 v[10:11], v[60:61], 0, v[54:55]
	v_mov_b32_e32 v12, v200
	v_rcp_f32_e32 v8, v8
	s_waitcnt vmcnt(0)
	v_fma_f32 v0, v9, v12, v0
	v_mul_f32_e32 v86, v0, v8
	v_mov_b32_e32 v0, v201
	s_waitcnt vmcnt(0)
	v_fma_f32 v0, v9, v0, v4
	v_mul_f32_e32 v87, v0, v8
	v_mul_f32_e32 v0, v87, v87
	v_fmac_f32_e32 v0, v86, v86
	s_nop 1
	v_add_f32_dpp v0, v0, v0 quad_perm:[1,0,3,2] row_mask:0xf bank_mask:0xf bound_ctrl:1
	s_nop 1
	v_add_f32_dpp v0, v0, v0 quad_perm:[2,3,0,1] row_mask:0xf bank_mask:0xf bound_ctrl:1
	s_nop 1
	v_add_f32_dpp v0, v0, v0 row_half_mirror row_mask:0xf bank_mask:0xf bound_ctrl:1
	s_nop 1
	v_mov_b32_dpp v4, v0 row_mirror row_mask:0xf bank_mask:0xf bound_ctrl:1
	s_and_saveexec_b64 s[14:15], vcc
	v_add_f32_e32 v0, v0, v4
	ds_write_b32 v39, v0 offset:10944
	s_or_b64 exec, exec, s[14:15]
	v_add_u32_e32 v0, 0xc4, v62
	ds_read2st64_b32 v[8:9], v0 offset0:38 offset1:39
	ds_read2st64_b32 v[10:11], v0 offset0:40 offset1:41
	v_or3_b32 v4, v66, s24, 49
	v_lshlrev_b32_e32 v32, 12, v4
	v_mov_b32_e32 v33, v169
	s_waitcnt lgkmcnt(1)
	v_mul_f32_e32 v0, 0xbfb8aa3b, v8
	v_exp_f32_e32 v0, v0
	s_waitcnt lgkmcnt(0)
	v_fmac_f32_e32 v10, v9, v11
	v_max_f32_e64 v0, |v10|, v0
	v_lshl_add_u64 v[10:11], v[60:61], 0, v[32:33]
	v_mov_b32_e32 v4, v202
	v_rcp_f32_e32 v0, v0
	s_waitcnt vmcnt(0)
	v_fma_f32 v1, v9, v4, v1
	v_mul_f32_e32 v65, v1, v0
	v_mov_b32_e32 v1, v203
	s_waitcnt vmcnt(0)
	v_fma_f32 v1, v9, v1, v5
	v_mul_f32_e32 v64, v1, v0
	v_mul_f32_e32 v0, v64, v64
	v_fmac_f32_e32 v0, v65, v65
	s_nop 1
	v_add_f32_dpp v0, v0, v0 quad_perm:[1,0,3,2] row_mask:0xf bank_mask:0xf bound_ctrl:1
	s_nop 1
	v_add_f32_dpp v0, v0, v0 quad_perm:[2,3,0,1] row_mask:0xf bank_mask:0xf bound_ctrl:1
	s_nop 1
	v_add_f32_dpp v0, v0, v0 row_half_mirror row_mask:0xf bank_mask:0xf bound_ctrl:1
	s_nop 1
	v_mov_b32_dpp v1, v0 row_mirror row_mask:0xf bank_mask:0xf bound_ctrl:1
	s_and_saveexec_b64 s[14:15], vcc
	v_add_f32_e32 v0, v0, v1
	ds_write_b32 v39, v0 offset:10948
	s_or_b64 exec, exec, s[14:15]
	v_add_u32_e32 v4, 0xc8, v62
	ds_read2st64_b32 v[0:1], v4 offset0:38 offset1:39
	ds_read2st64_b32 v[4:5], v4 offset0:40 offset1:41
	v_mov_b32_e32 v35, v169
	s_waitcnt lgkmcnt(1)
	v_mul_f32_e32 v0, 0xbfb8aa3b, v0
	v_exp_f32_e32 v0, v0
	s_waitcnt lgkmcnt(0)
	v_fmac_f32_e32 v4, v1, v5
	v_max_f32_e64 v0, |v4|, v0
	v_or3_b32 v4, v66, s24, 50
	v_lshlrev_b32_e32 v34, 12, v4
	v_lshl_add_u64 v[4:5], v[60:61], 0, v[34:35]
	v_mov_b32_e32 v8, v204
	v_rcp_f32_e32 v0, v0
	s_waitcnt vmcnt(0)
	v_fma_f32 v2, v1, v8, v2
	v_mul_f32_e32 v67, v2, v0
	v_mov_b32_e32 v2, v205
	s_waitcnt vmcnt(0)
	v_fma_f32 v1, v1, v2, v6
	v_mul_f32_e32 v68, v1, v0
	v_mul_f32_e32 v0, v68, v68
	v_fmac_f32_e32 v0, v67, v67
	s_nop 1
	v_add_f32_dpp v0, v0, v0 quad_perm:[1,0,3,2] row_mask:0xf bank_mask:0xf bound_ctrl:1
	s_nop 1
	v_add_f32_dpp v0, v0, v0 quad_perm:[2,3,0,1] row_mask:0xf bank_mask:0xf bound_ctrl:1
	s_nop 1
	v_add_f32_dpp v0, v0, v0 row_half_mirror row_mask:0xf bank_mask:0xf bound_ctrl:1
	s_nop 1
	v_mov_b32_dpp v1, v0 row_mirror row_mask:0xf bank_mask:0xf bound_ctrl:1
	s_and_saveexec_b64 s[14:15], vcc
	v_add_f32_e32 v0, v0, v1
	ds_write_b32 v39, v0 offset:10952
	s_or_b64 exec, exec, s[14:15]
	v_or3_b32 v0, v66, s24, 51
	v_lshlrev_b32_e32 v168, 12, v0
	v_lshl_add_u64 v[0:1], v[60:61], 0, v[168:169]
	v_mov_b32_e32 v2, v206
	v_mov_b32_e32 v6, v207
	v_add_u32_e32 v4, 0xcc, v62
	ds_read2st64_b32 v[0:1], v4 offset0:38 offset1:39
	ds_read2st64_b32 v[4:5], v4 offset0:40 offset1:41
	s_waitcnt lgkmcnt(1)
	v_mul_f32_e32 v0, 0xbfb8aa3b, v0
	v_exp_f32_e32 v0, v0
	s_waitcnt lgkmcnt(0)
	v_fmac_f32_e32 v4, v1, v5
	v_max_f32_e64 v0, |v4|, v0
	v_rcp_f32_e32 v0, v0
	s_waitcnt vmcnt(1)
	v_fmac_f32_e32 v3, v1, v2
	s_waitcnt vmcnt(0)
	v_fmac_f32_e32 v7, v1, v6
	v_mul_f32_e32 v60, v7, v0
	v_mul_f32_e32 v66, v3, v0
	v_mul_f32_e32 v0, v60, v60
	v_fmac_f32_e32 v0, v66, v66
	s_nop 1
	v_add_f32_dpp v0, v0, v0 quad_perm:[1,0,3,2] row_mask:0xf bank_mask:0xf bound_ctrl:1
	s_nop 1
	v_add_f32_dpp v0, v0, v0 quad_perm:[2,3,0,1] row_mask:0xf bank_mask:0xf bound_ctrl:1
	s_nop 1
	v_add_f32_dpp v0, v0, v0 row_half_mirror row_mask:0xf bank_mask:0xf bound_ctrl:1
	s_nop 1
	v_mov_b32_dpp v1, v0 row_mirror row_mask:0xf bank_mask:0xf bound_ctrl:1
	s_and_saveexec_b64 s[14:15], vcc
	s_cbranch_execz .LBB0_162
	v_add_f32_e32 v0, v0, v1
	ds_write_b32 v39, v0 offset:10956
	s_branch .LBB0_162

.LBB0_664:
	v_readlane_b32 s73, v255, 13
	s_mov_b32 s2, s73
	s_waitcnt lgkmcnt(0)
	s_load_dwordx2 s[4:5], s[0:1], 0x168
	v_lshl_add_u32 v32, s2, 3, v129
	v_readlane_b32 s6, v255, 33
	v_readlane_b32 s7, v255, 34
	s_movk_i32 s89, 0x2000
	s_waitcnt lgkmcnt(0)
	s_mov_b32 s2, s4
	s_mov_b32 s54, s4
	s_load_dwordx2 s[4:5], s[0:1], 0x150
	v_readlane_b32 s64, v255, 50
	v_and_b32_e32 v34, 0xfc, v138
	s_lshl_b32 s8, s2, 3
	s_mov_b64 s[10:11], -1
	s_andn2_b64 vcc, exec, s[6:7]
	v_cmp_gt_i32_e64 s[6:7], s89, v32
	s_movk_i32 s74, 0x1fff
	v_readlane_b32 s75, v255, 12
	v_readlane_b32 s53, v255, 49
	v_readlane_b32 s65, v255, 51
	v_readlane_b32 s66, v255, 52
	s_cbranch_vccnz .LBB0_669
	s_and_saveexec_b64 s[10:11], s[6:7]
	s_cbranch_execz .LBB0_668
	v_ashrrev_i32_e32 v33, 31, v32
	v_lshlrev_b64 v[0:1], 12, v[32:33]
	v_and_b32_e32 v2, 63, v128
	v_lshl_or_b32 v0, v2, 3, v0
	s_waitcnt lgkmcnt(0)
	v_lshl_add_u64 v[0:1], s[4:5], 0, v[0:1]
	s_mov_b64 s[6:7], 0x9640e00
	v_lshl_add_u64 v[36:37], v[0:1], 0, s[6:7]
	s_ashr_i32 s9, s8, 31
	v_lshlrev_b64 v[38:39], 13, v[32:33]
	v_lshlrev_b32_e32 v0, 4, v2
	s_movk_i32 s2, 0x1c00
	s_lshl_b64 s[6:7], s[8:9], 12
	v_or3_b32 v38, v38, v0, s2
	s_lshl_b64 s[12:13], s[8:9], 13
	s_mov_b64 s[14:15], 0
	v_lshlrev_b32_e32 v168, 2, v34
	s_load_dwordx2 s[16:17], s[0:1], 0x10
	s_waitcnt lgkmcnt(0)
	s_add_u32 s16, s16, s64
	s_addc_u32 s17, s17, s65
	global_load_dwordx4 v[88:91], v168, s[16:17]
	global_load_dwordx4 v[92:95], v168, s[16:17] offset:1024
	global_load_dwordx4 v[96:99], v168, s[16:17] offset:2048
	global_load_dwordx4 v[100:103], v168, s[16:17] offset:3072
	s_add_u32 s16, s16, 0x1000
	s_addc_u32 s17, s17, 0
	global_load_dwordx4 v[104:107], v168, s[16:17]
	global_load_dwordx4 v[108:111], v168, s[16:17] offset:1024
	global_load_dwordx4 v[112:115], v168, s[16:17] offset:2048
	global_load_dwordx4 v[116:119], v168, s[16:17] offset:3072
	v_mov_b32_e32 v33, v32
.LBB0_667:
	s_load_dwordx2 s[18:19], s[0:1], 0x148
	s_waitcnt lgkmcnt(0)
	v_lshl_add_u64 v[0:1], s[18:19], 0, v[38:39]
	v_add_u32_e32 v33, s8, v33
	v_add_co_u32_e32 v2, vcc, 0xfffff000, v0
	s_nop 1
	v_addc_co_u32_e32 v3, vcc, -1, v1, vcc
	global_load_dwordx4 v[56:59], v[2:3], off offset:-3072
	global_load_dwordx4 v[60:63], v[2:3], off offset:-2048
	global_load_dwordx4 v[64:67], v[2:3], off offset:-1024
	global_load_dwordx4 v[68:71], v[0:1], off offset:-4096
	global_load_dwordx4 v[72:75], v[0:1], off offset:-3072
	global_load_dwordx4 v[76:79], v[0:1], off offset:-2048
	global_load_dwordx4 v[80:83], v[0:1], off offset:-1024
	global_load_dwordx4 v[84:87], v[0:1], off
	v_lshl_add_u64 v[38:39], v[38:39], 0, s[12:13]
	v_cmp_lt_i32_e32 vcc, s74, v33
	s_or_b64 s[14:15], vcc, s[14:15]
	s_waitcnt vmcnt(0)
	v_mul_f32_e32 v121, v57, v57
	v_mul_f32_e32 v122, v59, v59
	v_fma_f32 v121, v56, v56, v121
	v_fma_f32 v122, v58, v58, v122
	v_add_f32_e32 v121, v121, v122
	v_mov_b32_e32 v120, v121
	v_mul_f32_e32 v121, v61, v61
	v_mul_f32_e32 v122, v63, v63
	v_fma_f32 v121, v60, v60, v121
	v_fma_f32 v122, v62, v62, v122
	v_add_f32_e32 v121, v121, v122
	v_add_f32_e32 v120, v120, v121
	v_mul_f32_e32 v121, v65, v65
	v_mul_f32_e32 v122, v67, v67
	v_fma_f32 v121, v64, v64, v121
	v_fma_f32 v122, v66, v66, v122
	v_add_f32_e32 v121, v121, v122
	v_add_f32_e32 v120, v120, v121
	v_mul_f32_e32 v121, v69, v69
	v_mul_f32_e32 v122, v71, v71
	v_fma_f32 v121, v68, v68, v121
	v_fma_f32 v122, v70, v70, v122
	v_add_f32_e32 v121, v121, v122
	v_add_f32_e32 v120, v120, v121
	v_mul_f32_e32 v121, v73, v73
	v_mul_f32_e32 v122, v75, v75
	v_fma_f32 v121, v72, v72, v121
	v_fma_f32 v122, v74, v74, v122
	v_add_f32_e32 v121, v121, v122
	v_add_f32_e32 v120, v120, v121
	v_mul_f32_e32 v121, v77, v77
	v_mul_f32_e32 v122, v79, v79
	v_fma_f32 v121, v76, v76, v121
	v_fma_f32 v122, v78, v78, v122
	v_add_f32_e32 v121, v121, v122
	v_add_f32_e32 v120, v120, v121
	v_mul_f32_e32 v121, v81, v81
	v_mul_f32_e32 v122, v83, v83
	v_fma_f32 v121, v80, v80, v121
	v_fma_f32 v122, v82, v82, v122
	v_add_f32_e32 v121, v121, v122
	v_add_f32_e32 v120, v120, v121
	v_mul_f32_e32 v121, v85, v85
	v_mul_f32_e32 v122, v87, v87
	v_fma_f32 v121, v84, v84, v121
	v_fma_f32 v122, v86, v86, v122
	v_add_f32_e32 v121, v121, v122
	v_add_f32_e32 v120, v120, v121
	s_nop 1
	v_add_f32_dpp v120, v120, v120 quad_perm:[1,0,3,2] row_mask:0xf bank_mask:0xf bound_ctrl:1
	s_nop 1
	v_add_f32_dpp v120, v120, v120 quad_perm:[2,3,0,1] row_mask:0xf bank_mask:0xf bound_ctrl:1
	s_nop 1
	v_add_f32_dpp v120, v120, v120 row_half_mirror row_mask:0xf bank_mask:0xf bound_ctrl:1
	s_nop 1
	v_add_f32_dpp v120, v120, v120 row_mirror row_mask:0xf bank_mask:0xf bound_ctrl:1
	s_nop 1
	v_readlane_b32 s2, v120, 16
	v_readlane_b32 s9, v120, 48
	v_readlane_b32 s18, v120, 0
	v_readlane_b32 s19, v120, 32
	v_mov_b32_e32 v122, s2
	v_mov_b32_e32 v123, s9
	v_pk_add_f32 v[122:123], s[18:19], v[122:123]
	s_nop 0
	v_add_f32_e32 v120, v122, v123
	v_fmamk_f32 v120, v120, 0x3a000000, v227
	v_cmp_gt_f32_e32 vcc, s29, v120
	v_mul_f32_e32 v121, 0x4b800000, v120
	s_nop 0
	v_cndmask_b32_e32 v120, v120, v121, vcc
	v_rsq_f32_e32 v120, v120
	s_nop 0
	v_mul_f32_e32 v121, 0x45800000, v120
	v_cndmask_b32_e32 v120, v120, v121, vcc
	v_pk_mul_f32 v[140:141], v[56:57], v[120:121] op_sel_hi:[1,0]
	v_pk_mul_f32 v[142:143], v[58:59], v[120:121] op_sel_hi:[1,0]
	v_pk_mul_f32 v[140:141], v[140:141], v[88:89]
	v_pk_mul_f32 v[142:143], v[142:143], v[90:91]
	v_cvt_pk_bf16_f32 v144, v140, v141
	v_cvt_pk_bf16_f32 v145, v142, v143
	global_store_dwordx2 v[36:37], v[144:145], off offset:-3584
	v_pk_mul_f32 v[146:147], v[60:61], v[120:121] op_sel_hi:[1,0]
	v_pk_mul_f32 v[148:149], v[62:63], v[120:121] op_sel_hi:[1,0]
	v_pk_mul_f32 v[146:147], v[146:147], v[92:93]
	v_pk_mul_f32 v[148:149], v[148:149], v[94:95]
	v_cvt_pk_bf16_f32 v150, v146, v147
	v_cvt_pk_bf16_f32 v151, v148, v149
	global_store_dwordx2 v[36:37], v[150:151], off offset:-3072
	v_pk_mul_f32 v[140:141], v[64:65], v[120:121] op_sel_hi:[1,0]
	v_pk_mul_f32 v[142:143], v[66:67], v[120:121] op_sel_hi:[1,0]
	v_pk_mul_f32 v[140:141], v[140:141], v[96:97]
	v_pk_mul_f32 v[142:143], v[142:143], v[98:99]
	v_cvt_pk_bf16_f32 v144, v140, v141
	v_cvt_pk_bf16_f32 v145, v142, v143
	global_store_dwordx2 v[36:37], v[144:145], off offset:-2560
	v_pk_mul_f32 v[146:147], v[68:69], v[120:121] op_sel_hi:[1,0]
	v_pk_mul_f32 v[148:149], v[70:71], v[120:121] op_sel_hi:[1,0]
	v_pk_mul_f32 v[146:147], v[146:147], v[100:101]
	v_pk_mul_f32 v[148:149], v[148:149], v[102:103]
	v_cvt_pk_bf16_f32 v150, v146, v147
	v_cvt_pk_bf16_f32 v151, v148, v149
	global_store_dwordx2 v[36:37], v[150:151], off offset:-2048
	v_pk_mul_f32 v[140:141], v[72:73], v[120:121] op_sel_hi:[1,0]
	v_pk_mul_f32 v[142:143], v[74:75], v[120:121] op_sel_hi:[1,0]
	v_pk_mul_f32 v[140:141], v[140:141], v[104:105]
	v_pk_mul_f32 v[142:143], v[142:143], v[106:107]
	v_cvt_pk_bf16_f32 v144, v140, v141
	v_cvt_pk_bf16_f32 v145, v142, v143
	global_store_dwordx2 v[36:37], v[144:145], off offset:-1536
	v_pk_mul_f32 v[146:147], v[76:77], v[120:121] op_sel_hi:[1,0]
	v_pk_mul_f32 v[148:149], v[78:79], v[120:121] op_sel_hi:[1,0]
	v_pk_mul_f32 v[146:147], v[146:147], v[108:109]
	v_pk_mul_f32 v[148:149], v[148:149], v[110:111]
	v_cvt_pk_bf16_f32 v150, v146, v147
	v_cvt_pk_bf16_f32 v151, v148, v149
	global_store_dwordx2 v[36:37], v[150:151], off offset:-1024
	v_pk_mul_f32 v[140:141], v[80:81], v[120:121] op_sel_hi:[1,0]
	v_pk_mul_f32 v[142:143], v[82:83], v[120:121] op_sel_hi:[1,0]
	v_pk_mul_f32 v[140:141], v[140:141], v[112:113]
	v_pk_mul_f32 v[142:143], v[142:143], v[114:115]
	v_cvt_pk_bf16_f32 v144, v140, v141
	v_cvt_pk_bf16_f32 v145, v142, v143
	global_store_dwordx2 v[36:37], v[144:145], off offset:-512
	v_pk_mul_f32 v[146:147], v[84:85], v[120:121] op_sel_hi:[1,0]
	v_pk_mul_f32 v[148:149], v[86:87], v[120:121] op_sel_hi:[1,0]
	v_pk_mul_f32 v[146:147], v[146:147], v[116:117]
	v_pk_mul_f32 v[148:149], v[148:149], v[118:119]
	v_cvt_pk_bf16_f32 v150, v146, v147
	v_cvt_pk_bf16_f32 v151, v148, v149
	global_store_dwordx2 v[36:37], v[150:151], off
	v_lshl_add_u64 v[36:37], v[36:37], 0, s[6:7]
	s_andn2_b64 exec, exec, s[14:15]
	s_cbranch_execnz .LBB0_667

.LBB0_673:
	s_or_b64 exec, exec, s[10:11]
	s_waitcnt lgkmcnt(0)
	s_load_dwordx2 s[6:7], s[0:1], 0x0
	v_cmp_gt_i32_e32 vcc, s89, v32
	s_and_saveexec_b64 s[10:11], vcc
	s_cbranch_execz .LBB0_676
	v_ashrrev_i32_e32 v33, 31, v32
	v_lshlrev_b64 v[0:1], 12, v[32:33]
	v_and_b32_e32 v2, 63, v128
	v_lshl_or_b32 v0, v2, 3, v0
	v_lshl_add_u64 v[0:1], s[4:5], 0, v[0:1]
	s_mov_b64 s[4:5], 0x9640e00
	v_lshl_add_u64 v[36:37], v[0:1], 0, s[4:5]
	s_ashr_i32 s9, s8, 31
	v_lshlrev_b64 v[38:39], 13, v[32:33]
	v_lshlrev_b32_e32 v0, 4, v2
	s_movk_i32 s2, 0x1c00
	s_lshl_b64 s[4:5], s[8:9], 12
	v_or3_b32 v38, v38, v0, s2
	s_lshl_b64 s[12:13], s[8:9], 13
	s_mov_b64 s[14:15], 0
	v_lshlrev_b32_e32 v168, 2, v34
	s_load_dwordx2 s[16:17], s[0:1], 0x10
	s_waitcnt lgkmcnt(0)
	global_load_dwordx4 v[88:91], v168, s[16:17]
	global_load_dwordx4 v[92:95], v168, s[16:17] offset:1024
	global_load_dwordx4 v[96:99], v168, s[16:17] offset:2048
	global_load_dwordx4 v[100:103], v168, s[16:17] offset:3072
	s_add_u32 s16, s16, 0x1000
	s_addc_u32 s17, s17, 0
	global_load_dwordx4 v[104:107], v168, s[16:17]
	global_load_dwordx4 v[108:111], v168, s[16:17] offset:1024
	global_load_dwordx4 v[112:115], v168, s[16:17] offset:2048
	global_load_dwordx4 v[116:119], v168, s[16:17] offset:3072
.LBB0_675:
	s_load_dwordx2 s[16:17], s[0:1], 0x148
	s_waitcnt lgkmcnt(0)
	v_lshl_add_u64 v[0:1], s[6:7], 0, v[38:39]
	v_lshl_add_u64 v[4:5], s[16:17], 0, v[38:39]
	v_add_u32_e32 v32, s8, v32
	v_add_co_u32_e32 v2, vcc, 0xfffff000, v0
	s_nop 1
	v_addc_co_u32_e32 v3, vcc, -1, v1, vcc
	global_load_dwordx4 v[56:59], v[2:3], off offset:-3072
	global_load_dwordx4 v[60:63], v[2:3], off offset:-2048
	global_load_dwordx4 v[64:67], v[2:3], off offset:-1024
	global_load_dwordx4 v[68:71], v[0:1], off offset:-4096
	global_load_dwordx4 v[72:75], v[0:1], off offset:-3072
	global_load_dwordx4 v[76:79], v[0:1], off offset:-2048
	global_load_dwordx4 v[80:83], v[0:1], off offset:-1024
	global_load_dwordx4 v[84:87], v[0:1], off
	v_add_co_u32_e32 v6, vcc, 0xfffff000, v4
	s_nop 1
	v_addc_co_u32_e32 v7, vcc, -1, v5, vcc
	v_lshl_add_u64 v[38:39], v[38:39], 0, s[12:13]
	v_cmp_lt_i32_e32 vcc, s74, v32
	s_or_b64 s[14:15], vcc, s[14:15]
	s_waitcnt vmcnt(0)
	global_store_dwordx4 v[6:7], v[56:59], off offset:-3072
	global_store_dwordx4 v[6:7], v[60:63], off offset:-2048
	global_store_dwordx4 v[6:7], v[64:67], off offset:-1024
	global_store_dwordx4 v[4:5], v[68:71], off offset:-4096
	global_store_dwordx4 v[4:5], v[72:75], off offset:-3072
	global_store_dwordx4 v[4:5], v[76:79], off offset:-2048
	global_store_dwordx4 v[4:5], v[80:83], off offset:-1024
	global_store_dwordx4 v[4:5], v[84:87], off
	v_mul_f32_e32 v121, v57, v57
	v_mul_f32_e32 v122, v59, v59
	v_fma_f32 v121, v56, v56, v121
	v_fma_f32 v122, v58, v58, v122
	v_add_f32_e32 v121, v121, v122
	v_mov_b32_e32 v120, v121
	v_mul_f32_e32 v121, v61, v61
	v_mul_f32_e32 v122, v63, v63
	v_fma_f32 v121, v60, v60, v121
	v_fma_f32 v122, v62, v62, v122
	v_add_f32_e32 v121, v121, v122
	v_add_f32_e32 v120, v120, v121
	v_mul_f32_e32 v121, v65, v65
	v_mul_f32_e32 v122, v67, v67
	v_fma_f32 v121, v64, v64, v121
	v_fma_f32 v122, v66, v66, v122
	v_add_f32_e32 v121, v121, v122
	v_add_f32_e32 v120, v120, v121
	v_mul_f32_e32 v121, v69, v69
	v_mul_f32_e32 v122, v71, v71
	v_fma_f32 v121, v68, v68, v121
	v_fma_f32 v122, v70, v70, v122
	v_add_f32_e32 v121, v121, v122
	v_add_f32_e32 v120, v120, v121
	v_mul_f32_e32 v121, v73, v73
	v_mul_f32_e32 v122, v75, v75
	v_fma_f32 v121, v72, v72, v121
	v_fma_f32 v122, v74, v74, v122
	v_add_f32_e32 v121, v121, v122
	v_add_f32_e32 v120, v120, v121
	v_mul_f32_e32 v121, v77, v77
	v_mul_f32_e32 v122, v79, v79
	v_fma_f32 v121, v76, v76, v121
	v_fma_f32 v122, v78, v78, v122
	v_add_f32_e32 v121, v121, v122
	v_add_f32_e32 v120, v120, v121
	v_mul_f32_e32 v121, v81, v81
	v_mul_f32_e32 v122, v83, v83
	v_fma_f32 v121, v80, v80, v121
	v_fma_f32 v122, v82, v82, v122
	v_add_f32_e32 v121, v121, v122
	v_add_f32_e32 v120, v120, v121
	v_mul_f32_e32 v121, v85, v85
	v_mul_f32_e32 v122, v87, v87
	v_fma_f32 v121, v84, v84, v121
	v_fma_f32 v122, v86, v86, v122
	v_add_f32_e32 v121, v121, v122
	v_add_f32_e32 v120, v120, v121
	s_nop 1
	v_add_f32_dpp v120, v120, v120 quad_perm:[1,0,3,2] row_mask:0xf bank_mask:0xf bound_ctrl:1
	s_nop 1
	v_add_f32_dpp v120, v120, v120 quad_perm:[2,3,0,1] row_mask:0xf bank_mask:0xf bound_ctrl:1
	s_nop 1
	v_add_f32_dpp v120, v120, v120 row_half_mirror row_mask:0xf bank_mask:0xf bound_ctrl:1
	s_nop 1
	v_add_f32_dpp v120, v120, v120 row_mirror row_mask:0xf bank_mask:0xf bound_ctrl:1
	s_nop 1
	v_readlane_b32 s2, v120, 16
	v_readlane_b32 s9, v120, 48
	v_readlane_b32 s18, v120, 0
	v_readlane_b32 s19, v120, 32
	v_mov_b32_e32 v122, s2
	v_mov_b32_e32 v123, s9
	v_pk_add_f32 v[122:123], s[18:19], v[122:123]
	s_nop 0
	v_add_f32_e32 v120, v122, v123
	v_fmamk_f32 v120, v120, 0x3a000000, v227
	v_cmp_gt_f32_e32 vcc, s29, v120
	v_mul_f32_e32 v121, 0x4b800000, v120
	s_nop 0
	v_cndmask_b32_e32 v120, v120, v121, vcc
	v_rsq_f32_e32 v120, v120
	s_nop 0
	v_mul_f32_e32 v121, 0x45800000, v120
	v_cndmask_b32_e32 v120, v120, v121, vcc
	v_pk_mul_f32 v[140:141], v[56:57], v[120:121] op_sel_hi:[1,0]
	v_pk_mul_f32 v[142:143], v[58:59], v[120:121] op_sel_hi:[1,0]
	v_pk_mul_f32 v[140:141], v[140:141], v[88:89]
	v_pk_mul_f32 v[142:143], v[142:143], v[90:91]
	v_cvt_pk_bf16_f32 v144, v140, v141
	v_cvt_pk_bf16_f32 v145, v142, v143
	global_store_dwordx2 v[36:37], v[144:145], off offset:-3584
	v_pk_mul_f32 v[146:147], v[60:61], v[120:121] op_sel_hi:[1,0]
	v_pk_mul_f32 v[148:149], v[62:63], v[120:121] op_sel_hi:[1,0]
	v_pk_mul_f32 v[146:147], v[146:147], v[92:93]
	v_pk_mul_f32 v[148:149], v[148:149], v[94:95]
	v_cvt_pk_bf16_f32 v150, v146, v147
	v_cvt_pk_bf16_f32 v151, v148, v149
	global_store_dwordx2 v[36:37], v[150:151], off offset:-3072
	v_pk_mul_f32 v[140:141], v[64:65], v[120:121] op_sel_hi:[1,0]
	v_pk_mul_f32 v[142:143], v[66:67], v[120:121] op_sel_hi:[1,0]
	v_pk_mul_f32 v[140:141], v[140:141], v[96:97]
	v_pk_mul_f32 v[142:143], v[142:143], v[98:99]
	v_cvt_pk_bf16_f32 v144, v140, v141
	v_cvt_pk_bf16_f32 v145, v142, v143
	global_store_dwordx2 v[36:37], v[144:145], off offset:-2560
	v_pk_mul_f32 v[146:147], v[68:69], v[120:121] op_sel_hi:[1,0]
	v_pk_mul_f32 v[148:149], v[70:71], v[120:121] op_sel_hi:[1,0]
	v_pk_mul_f32 v[146:147], v[146:147], v[100:101]
	v_pk_mul_f32 v[148:149], v[148:149], v[102:103]
	v_cvt_pk_bf16_f32 v150, v146, v147
	v_cvt_pk_bf16_f32 v151, v148, v149
	global_store_dwordx2 v[36:37], v[150:151], off offset:-2048
	v_pk_mul_f32 v[140:141], v[72:73], v[120:121] op_sel_hi:[1,0]
	v_pk_mul_f32 v[142:143], v[74:75], v[120:121] op_sel_hi:[1,0]
	v_pk_mul_f32 v[140:141], v[140:141], v[104:105]
	v_pk_mul_f32 v[142:143], v[142:143], v[106:107]
	v_cvt_pk_bf16_f32 v144, v140, v141
	v_cvt_pk_bf16_f32 v145, v142, v143
	global_store_dwordx2 v[36:37], v[144:145], off offset:-1536
	v_pk_mul_f32 v[146:147], v[76:77], v[120:121] op_sel_hi:[1,0]
	v_pk_mul_f32 v[148:149], v[78:79], v[120:121] op_sel_hi:[1,0]
	v_pk_mul_f32 v[146:147], v[146:147], v[108:109]
	v_pk_mul_f32 v[148:149], v[148:149], v[110:111]
	v_cvt_pk_bf16_f32 v150, v146, v147
	v_cvt_pk_bf16_f32 v151, v148, v149
	global_store_dwordx2 v[36:37], v[150:151], off offset:-1024
	v_pk_mul_f32 v[140:141], v[80:81], v[120:121] op_sel_hi:[1,0]
	v_pk_mul_f32 v[142:143], v[82:83], v[120:121] op_sel_hi:[1,0]
	v_pk_mul_f32 v[140:141], v[140:141], v[112:113]
	v_pk_mul_f32 v[142:143], v[142:143], v[114:115]
	v_cvt_pk_bf16_f32 v144, v140, v141
	v_cvt_pk_bf16_f32 v145, v142, v143
	global_store_dwordx2 v[36:37], v[144:145], off offset:-512
	v_pk_mul_f32 v[146:147], v[84:85], v[120:121] op_sel_hi:[1,0]
	v_pk_mul_f32 v[148:149], v[86:87], v[120:121] op_sel_hi:[1,0]
	v_pk_mul_f32 v[146:147], v[146:147], v[116:117]
	v_pk_mul_f32 v[148:149], v[148:149], v[118:119]
	v_cvt_pk_bf16_f32 v150, v146, v147
	v_cvt_pk_bf16_f32 v151, v148, v149
	global_store_dwordx2 v[36:37], v[150:151], off
	v_lshl_add_u64 v[36:37], v[36:37], 0, s[4:5]
	s_andn2_b64 exec, exec, s[14:15]
	s_cbranch_execnz .LBB0_675

.LBB0_869:
	v_add_co_u32_e32 v76, vcc, 0xffffd000, v66
	s_movk_i32 s8, 0xe000
	s_nop 0
	v_addc_co_u32_e32 v77, vcc, -1, v67, vcc
	v_add_co_u32_e32 v86, vcc, s8, v66
	s_movk_i32 s8, 0xf000
	s_nop 0
	v_addc_co_u32_e32 v87, vcc, -1, v67, vcc
	v_add_co_u32_e32 v138, vcc, s8, v66
	global_load_dwordx2 v[78:79], v[76:77], off offset:-3072
	global_load_dwordx2 v[80:81], v[76:77], off offset:-2048
	global_load_dwordx2 v[82:83], v[76:77], off offset:-1024
	global_load_dwordx2 v[84:85], v[76:77], off
	v_addc_co_u32_e32 v139, vcc, -1, v67, vcc
	global_load_dwordx2 v[130:131], v[86:87], off offset:-3072
	global_load_dwordx2 v[132:133], v[86:87], off offset:-2048
	global_load_dwordx2 v[134:135], v[86:87], off offset:-1024
	global_load_dwordx2 v[136:137], v[86:87], off
	global_load_dwordx2 v[140:141], v[138:139], off offset:-3072
	global_load_dwordx2 v[142:143], v[138:139], off offset:-2048
	global_load_dwordx2 v[144:145], v[138:139], off offset:-1024
	global_load_dwordx2 v[146:147], v[66:67], off offset:-4096
	global_load_dwordx2 v[148:149], v[66:67], off offset:-3072
	global_load_dwordx2 v[74:75], v[66:67], off offset:-2048
	global_load_dwordx2 v[70:71], v[66:67], off offset:-1024
	global_load_dwordx2 v[176:177], v[76:77], off offset:-3584
	global_load_dwordx2 v[178:179], v[76:77], off offset:-2560
	global_load_dwordx2 v[180:181], v[76:77], off offset:-1536
	global_load_dwordx2 v[182:183], v[76:77], off offset:-512
	global_load_dwordx2 v[184:185], v[86:87], off offset:-3584
	global_load_dwordx2 v[186:187], v[86:87], off offset:-2560
	global_load_dwordx2 v[188:189], v[86:87], off offset:-1536
	global_load_dwordx2 v[190:191], v[86:87], off offset:-512
	global_load_dwordx2 v[192:193], v[138:139], off offset:-3584
	global_load_dwordx2 v[194:195], v[138:139], off offset:-2560
	global_load_dwordx2 v[196:197], v[138:139], off offset:-1536
	global_load_dwordx2 v[198:199], v[138:139], off offset:-512
	global_load_dwordx2 v[200:201], v[66:67], off offset:-3584
	global_load_dwordx2 v[202:203], v[66:67], off offset:-2560
	global_load_dwordx2 v[204:205], v[66:67], off offset:-1536
	global_load_dwordx2 v[206:207], v[66:67], off offset:-512
	v_pk_mul_f32 v[152:153], v[60:61], v[72:73] op_sel:[0,1] op_sel_hi:[1,0]
	s_add_i32 s8, s2, 32
	v_pk_fma_f32 v[154:155], v[58:59], v[72:73], v[152:153] neg_lo:[0,0,1] neg_hi:[0,0,1]
	v_pk_fma_f32 v[72:73], v[58:59], v[72:73], v[152:153]
	s_add_i32 s2, s2, 64
	v_mov_b32_e32 v155, v73
	v_cmp_gt_u32_e32 vcc, s2, v51
	s_or_b64 s[6:7], vcc, s[6:7]
	s_mov_b32 s2, s8
	s_waitcnt vmcnt(0)
	v_mov_b32_e32 v150, v176
	v_mov_b32_e32 v151, v177
	v_pk_add_f32 v[72:73], v[150:151], v[154:155]
	s_nop 0
	v_pk_mul_f32 v[150:151], v[68:69], v[72:73]
	v_pk_mul_f32 v[72:73], v[64:65], v[72:73]
	v_sub_f32_e32 v39, v150, v151
	v_mov_b32_e32 v150, v178
	v_mov_b32_e32 v151, v179
	v_add_f32_e32 v78, v78, v39
	v_add_f32_e32 v39, v72, v73
	v_add_f32_e32 v72, v79, v39
	v_pk_mul_f32 v[72:73], v[64:65], v[72:73] op_sel_hi:[1,0]
	s_nop 0
	v_pk_fma_f32 v[152:153], v[68:69], v[78:79], v[72:73] neg_lo:[0,0,1] neg_hi:[0,0,1]
	v_pk_fma_f32 v[72:73], v[68:69], v[78:79], v[72:73] op_sel_hi:[1,0,1]
	s_nop 0
	v_mov_b32_e32 v153, v73
	s_waitcnt vmcnt(0)
	v_pk_add_f32 v[72:73], v[150:151], v[152:153]
	s_nop 0
	v_pk_mul_f32 v[78:79], v[68:69], v[72:73]
	v_pk_mul_f32 v[72:73], v[64:65], v[72:73]
	v_sub_f32_e32 v39, v78, v79
	v_add_f32_e32 v78, v80, v39
	v_add_f32_e32 v39, v72, v73
	v_add_f32_e32 v72, v81, v39
	v_mov_b32_e32 v80, v180
	v_mov_b32_e32 v81, v181
	v_pk_mul_f32 v[72:73], v[64:65], v[72:73] op_sel_hi:[1,0]
	v_mov_b32_e32 v76, v182
	v_mov_b32_e32 v77, v183
	v_pk_fma_f32 v[150:151], v[68:69], v[78:79], v[72:73] neg_lo:[0,0,1] neg_hi:[0,0,1]
	v_pk_fma_f32 v[72:73], v[68:69], v[78:79], v[72:73] op_sel_hi:[1,0,1]
	s_nop 0
	v_mov_b32_e32 v151, v73
	s_waitcnt vmcnt(1)
	v_pk_add_f32 v[72:73], v[80:81], v[150:151]
	s_nop 0
	v_pk_mul_f32 v[78:79], v[68:69], v[72:73]
	v_pk_mul_f32 v[72:73], v[64:65], v[72:73]
	v_sub_f32_e32 v39, v78, v79
	v_add_f32_e32 v78, v82, v39
	v_add_f32_e32 v39, v72, v73
	v_add_f32_e32 v72, v83, v39
	v_pk_mul_f32 v[72:73], v[64:65], v[72:73] op_sel_hi:[1,0]
	s_nop 0
	v_pk_fma_f32 v[80:81], v[68:69], v[78:79], v[72:73] neg_lo:[0,0,1] neg_hi:[0,0,1]
	v_pk_fma_f32 v[72:73], v[68:69], v[78:79], v[72:73] op_sel_hi:[1,0,1]
	v_mov_b32_e32 v78, v184
	v_mov_b32_e32 v79, v185
	v_mov_b32_e32 v81, v73
	s_waitcnt vmcnt(1)
	v_pk_add_f32 v[72:73], v[76:77], v[80:81]
	s_nop 0
	v_pk_mul_f32 v[76:77], v[68:69], v[72:73]
	v_pk_mul_f32 v[72:73], v[64:65], v[72:73]
	v_sub_f32_e32 v39, v76, v77
	v_add_f32_e32 v76, v84, v39
	v_add_f32_e32 v39, v72, v73
	v_add_f32_e32 v72, v85, v39
	v_pk_mul_f32 v[72:73], v[64:65], v[72:73] op_sel_hi:[1,0]
	s_nop 0
	v_pk_fma_f32 v[80:81], v[68:69], v[76:77], v[72:73] neg_lo:[0,0,1] neg_hi:[0,0,1]
	v_pk_fma_f32 v[72:73], v[68:69], v[76:77], v[72:73] op_sel_hi:[1,0,1]
	s_nop 0
	v_mov_b32_e32 v81, v73
	s_waitcnt vmcnt(0)
	v_pk_add_f32 v[72:73], v[78:79], v[80:81]
	v_mov_b32_e32 v78, v186
	v_mov_b32_e32 v79, v187
	v_pk_mul_f32 v[76:77], v[68:69], v[72:73]
	v_pk_mul_f32 v[72:73], v[64:65], v[72:73]
	v_sub_f32_e32 v39, v76, v77
	v_add_f32_e32 v76, v130, v39
	v_add_f32_e32 v39, v72, v73
	v_add_f32_e32 v72, v131, v39
	v_pk_mul_f32 v[72:73], v[64:65], v[72:73] op_sel_hi:[1,0]
	s_nop 0
	v_pk_fma_f32 v[80:81], v[68:69], v[76:77], v[72:73] neg_lo:[0,0,1] neg_hi:[0,0,1]
	v_pk_fma_f32 v[72:73], v[68:69], v[76:77], v[72:73] op_sel_hi:[1,0,1]
	s_nop 0
	v_mov_b32_e32 v81, v73
	s_waitcnt vmcnt(0)
	v_pk_add_f32 v[72:73], v[78:79], v[80:81]
	v_mov_b32_e32 v78, v188
	v_mov_b32_e32 v79, v189
	v_pk_mul_f32 v[76:77], v[68:69], v[72:73]
	v_pk_mul_f32 v[72:73], v[64:65], v[72:73]
	v_sub_f32_e32 v39, v76, v77
	v_add_f32_e32 v76, v132, v39
	v_add_f32_e32 v39, v72, v73
	v_add_f32_e32 v72, v133, v39
	v_pk_mul_f32 v[72:73], v[64:65], v[72:73] op_sel_hi:[1,0]
	s_nop 0
	v_pk_fma_f32 v[80:81], v[68:69], v[76:77], v[72:73] neg_lo:[0,0,1] neg_hi:[0,0,1]
	v_pk_fma_f32 v[72:73], v[68:69], v[76:77], v[72:73] op_sel_hi:[1,0,1]
	s_nop 0
	v_mov_b32_e32 v81, v73
	s_waitcnt vmcnt(0)
	v_pk_add_f32 v[72:73], v[78:79], v[80:81]
	v_mov_b32_e32 v78, v190
	v_mov_b32_e32 v79, v191
	v_pk_mul_f32 v[76:77], v[68:69], v[72:73]
	v_pk_mul_f32 v[72:73], v[64:65], v[72:73]
	v_sub_f32_e32 v39, v76, v77
	v_add_f32_e32 v76, v134, v39
	v_add_f32_e32 v39, v72, v73
	v_add_f32_e32 v72, v135, v39
	v_pk_mul_f32 v[72:73], v[64:65], v[72:73] op_sel_hi:[1,0]
	s_nop 0
	v_pk_fma_f32 v[80:81], v[68:69], v[76:77], v[72:73] neg_lo:[0,0,1] neg_hi:[0,0,1]
	v_pk_fma_f32 v[72:73], v[68:69], v[76:77], v[72:73] op_sel_hi:[1,0,1]
	s_nop 0
	v_mov_b32_e32 v81, v73
	s_waitcnt vmcnt(0)
	v_pk_add_f32 v[72:73], v[78:79], v[80:81]
	v_mov_b32_e32 v78, v192
	v_mov_b32_e32 v79, v193
	v_pk_mul_f32 v[76:77], v[68:69], v[72:73]
	v_pk_mul_f32 v[72:73], v[64:65], v[72:73]
	v_sub_f32_e32 v39, v76, v77
	v_add_f32_e32 v76, v136, v39
	v_add_f32_e32 v39, v72, v73
	v_add_f32_e32 v72, v137, v39
	v_pk_mul_f32 v[72:73], v[64:65], v[72:73] op_sel_hi:[1,0]
	s_nop 0
	v_pk_fma_f32 v[80:81], v[68:69], v[76:77], v[72:73] neg_lo:[0,0,1] neg_hi:[0,0,1]
	v_pk_fma_f32 v[72:73], v[68:69], v[76:77], v[72:73] op_sel_hi:[1,0,1]
	s_nop 0
	v_mov_b32_e32 v81, v73
	s_waitcnt vmcnt(0)
	v_pk_add_f32 v[72:73], v[78:79], v[80:81]
	v_mov_b32_e32 v78, v194
	v_mov_b32_e32 v79, v195
	v_pk_mul_f32 v[76:77], v[68:69], v[72:73]
	v_pk_mul_f32 v[72:73], v[64:65], v[72:73]
	v_sub_f32_e32 v39, v76, v77
	v_add_f32_e32 v76, v140, v39
	v_add_f32_e32 v39, v72, v73
	v_add_f32_e32 v72, v141, v39
	v_pk_mul_f32 v[72:73], v[64:65], v[72:73] op_sel_hi:[1,0]
	s_nop 0
	v_pk_fma_f32 v[80:81], v[68:69], v[76:77], v[72:73] neg_lo:[0,0,1] neg_hi:[0,0,1]
	v_pk_fma_f32 v[72:73], v[68:69], v[76:77], v[72:73] op_sel_hi:[1,0,1]
	s_nop 0
	v_mov_b32_e32 v81, v73
	s_waitcnt vmcnt(0)
	v_pk_add_f32 v[72:73], v[78:79], v[80:81]
	v_mov_b32_e32 v78, v196
	v_mov_b32_e32 v79, v197
	v_pk_mul_f32 v[76:77], v[68:69], v[72:73]
	v_pk_mul_f32 v[72:73], v[64:65], v[72:73]
	v_sub_f32_e32 v39, v76, v77
	v_add_f32_e32 v76, v142, v39
	v_add_f32_e32 v39, v72, v73
	v_add_f32_e32 v72, v143, v39
	v_pk_mul_f32 v[72:73], v[64:65], v[72:73] op_sel_hi:[1,0]
	s_nop 0
	v_pk_fma_f32 v[80:81], v[68:69], v[76:77], v[72:73] neg_lo:[0,0,1] neg_hi:[0,0,1]
	v_pk_fma_f32 v[72:73], v[68:69], v[76:77], v[72:73] op_sel_hi:[1,0,1]
	s_nop 0
	v_mov_b32_e32 v81, v73
	s_waitcnt vmcnt(0)
	v_pk_add_f32 v[72:73], v[78:79], v[80:81]
	v_mov_b32_e32 v78, v198
	v_mov_b32_e32 v79, v199
	v_pk_mul_f32 v[76:77], v[68:69], v[72:73]
	v_pk_mul_f32 v[72:73], v[64:65], v[72:73]
	v_sub_f32_e32 v39, v76, v77
	v_add_f32_e32 v76, v144, v39
	v_add_f32_e32 v39, v72, v73
	v_add_f32_e32 v72, v145, v39
	v_pk_mul_f32 v[72:73], v[64:65], v[72:73] op_sel_hi:[1,0]
	s_nop 0
	v_pk_fma_f32 v[80:81], v[68:69], v[76:77], v[72:73] neg_lo:[0,0,1] neg_hi:[0,0,1]
	v_pk_fma_f32 v[72:73], v[68:69], v[76:77], v[72:73] op_sel_hi:[1,0,1]
	s_nop 0
	v_mov_b32_e32 v81, v73
	s_waitcnt vmcnt(0)
	v_pk_add_f32 v[72:73], v[78:79], v[80:81]
	v_mov_b32_e32 v78, v200
	v_mov_b32_e32 v79, v201
	v_pk_mul_f32 v[76:77], v[68:69], v[72:73]
	v_pk_mul_f32 v[72:73], v[64:65], v[72:73]
	v_sub_f32_e32 v39, v76, v77
	v_add_f32_e32 v76, v146, v39
	v_add_f32_e32 v39, v72, v73
	v_add_f32_e32 v72, v147, v39
	v_pk_mul_f32 v[72:73], v[64:65], v[72:73] op_sel_hi:[1,0]
	s_nop 0
	v_pk_fma_f32 v[80:81], v[68:69], v[76:77], v[72:73] neg_lo:[0,0,1] neg_hi:[0,0,1]
	v_pk_fma_f32 v[72:73], v[68:69], v[76:77], v[72:73] op_sel_hi:[1,0,1]
	s_nop 0
	v_mov_b32_e32 v81, v73
	s_waitcnt vmcnt(0)
	v_pk_add_f32 v[76:77], v[78:79], v[80:81]
	v_mov_b32_e32 v78, v202
	v_mov_b32_e32 v79, v203
	v_pk_mul_f32 v[72:73], v[68:69], v[76:77]
	v_pk_mul_f32 v[76:77], v[64:65], v[76:77]
	v_sub_f32_e32 v39, v72, v73
	v_add_f32_e32 v72, v148, v39
	v_add_f32_e32 v39, v76, v77
	v_add_f32_e32 v76, v149, v39
	v_pk_mul_f32 v[76:77], v[64:65], v[76:77] op_sel_hi:[1,0]
	s_nop 0
	v_pk_fma_f32 v[80:81], v[68:69], v[72:73], v[76:77] neg_lo:[0,0,1] neg_hi:[0,0,1]
	v_pk_fma_f32 v[72:73], v[68:69], v[72:73], v[76:77] op_sel_hi:[1,0,1]
	s_nop 0
	v_mov_b32_e32 v81, v73
	s_waitcnt vmcnt(0)
	v_pk_add_f32 v[72:73], v[78:79], v[80:81]
	s_nop 0
	v_pk_mul_f32 v[76:77], v[68:69], v[72:73]
	v_pk_mul_f32 v[72:73], v[64:65], v[72:73]
	v_sub_f32_e32 v39, v76, v77
	v_mov_b32_e32 v76, v204
	v_mov_b32_e32 v77, v205
	v_add_f32_e32 v74, v74, v39
	v_add_f32_e32 v39, v72, v73
	v_add_f32_e32 v72, v75, v39
	v_pk_mul_f32 v[72:73], v[64:65], v[72:73] op_sel_hi:[1,0]
	s_nop 0
	v_pk_fma_f32 v[78:79], v[68:69], v[74:75], v[72:73] neg_lo:[0,0,1] neg_hi:[0,0,1]
	v_pk_fma_f32 v[72:73], v[68:69], v[74:75], v[72:73] op_sel_hi:[1,0,1]
	s_nop 0
	v_mov_b32_e32 v79, v73
	s_waitcnt vmcnt(0)
	v_pk_add_f32 v[72:73], v[76:77], v[78:79]
	s_nop 0
	v_pk_mul_f32 v[74:75], v[68:69], v[72:73]
	v_pk_mul_f32 v[72:73], v[64:65], v[72:73]
	v_sub_f32_e32 v39, v74, v75
	v_mov_b32_e32 v74, v206
	v_mov_b32_e32 v75, v207
	v_add_f32_e32 v70, v70, v39
	v_add_f32_e32 v39, v72, v73
	v_add_f32_e32 v72, v71, v39
	v_pk_mul_f32 v[72:73], v[64:65], v[72:73] op_sel_hi:[1,0]
	s_nop 0
	v_pk_fma_f32 v[76:77], v[68:69], v[70:71], v[72:73] neg_lo:[0,0,1] neg_hi:[0,0,1]
	v_pk_fma_f32 v[70:71], v[68:69], v[70:71], v[72:73] op_sel_hi:[1,0,1]
	s_nop 0
	v_mov_b32_e32 v77, v71
	s_waitcnt vmcnt(0)
	v_pk_add_f32 v[70:71], v[74:75], v[76:77]
	s_nop 0
	v_mul_f32_e32 v72, v69, v71
	v_mul_f32_e32 v74, v64, v70
	v_pk_fma_f32 v[72:73], v[68:69], v[70:71], v[72:73] op_sel_hi:[1,1,0] neg_lo:[0,0,1] neg_hi:[0,0,1]
	v_pk_fma_f32 v[70:71], v[64:65], v[70:71], v[74:75] op_sel_hi:[1,1,0]
	global_load_dwordx2 v[74:75], v[66:67], off
	v_mov_b32_e32 v73, v71
	v_lshl_add_u64 v[66:67], v[66:67], 0, s[40:41]
	v_mov_b32_e32 v70, s8
	s_waitcnt vmcnt(0)
	v_pk_add_f32 v[72:73], v[74:75], v[72:73]
	s_andn2_b64 exec, exec, s[6:7]
	s_cbranch_execnz .LBB0_869
	s_or_b64 exec, exec, s[6:7]
	v_pk_mov_b32 v[66:67], v[72:73], v[72:73] op_sel:[1,0]
